# per-wave address/mask setup of both coefficient passes and the GDN recurrence hoisted out of the 64-token block loops; RWKV first 8-token block skips the identity decay scaling; GDN MQ*T rows split ac
# baseline (speedup 1.0000x reference)
.LBB0_533:
	s_cmpk_gt_i32 s71, 0x7f
	s_mov_b64 s[0:1], -1
	s_cbranch_scc0 .LBB0_560
	s_add_i32 s3, s71, 0xffffff80
	v_mov_b32_e32 v1, v180
	s_lshl_b32 s0, s3, 8
	s_bfe_u32 s6, s71, 0x20001
	s_and_b32 s16, s0, 0x7800
	s_waitcnt vmcnt(2)
	v_ashrrev_i32_e32 v18, 3, v1
	s_lshl_b32 s72, s6, 2
	s_lshl_b32 s0, s6, 8
	v_add_u32_e32 v21, s16, v18
	v_mov_b64_e32 v[18:19], s[22:23]
	s_mov_b32 s1, s73
	s_add_u32 s8, s22, s0
	v_mad_i64_i32 v[18:19], s[4:5], v21, s83, v[18:19]
	s_addc_u32 s9, s23, 0
	v_lshl_add_u64 v[18:19], v[18:19], 0, s[0:1]
	s_lshl_b32 s0, s3, 6
	s_and_b32 s3, s0, 64
	v_mov_b32_e32 v2, s72
	v_lshlrev_b32_e32 v20, 4, v1
	s_lshl_b32 s0, s3, 1
	global_load_dword v24, v2, s[64:65]
	global_load_dword v124, v2, s[66:67]
	v_and_b32_e32 v25, 63, v1
	v_and_b32_e32 v2, 0xf0, v20
	v_lshl_add_u64 v[18:19], v[18:19], 0, s[0:1]
	v_and_b32_e32 v20, 0x70, v20
	v_mov_b32_e32 v21, v94
	v_mov_b32_e32 v3, v94
	v_add_u32_e32 v12, 0x200, v1
	v_lshl_add_u64 v[18:19], v[18:19], 0, v[20:21]
	v_or_b32_e32 v20, s16, v25
	v_lshl_add_u64 v[10:11], s[8:9], 0, v[2:3]
	v_ashrrev_i32_e32 v2, 4, v1
	v_ashrrev_i32_e32 v12, 4, v12
	v_mul_u32_u24_e32 v20, 0x88, v20
	v_add_u32_e32 v2, s16, v2
	v_add_u32_e32 v12, s16, v12
	v_lshlrev_b32_e32 v20, 2, v20
	v_mad_i64_i32 v[6:7], s[4:5], v2, s83, v[10:11]
	v_mad_i64_i32 v[14:15], s[4:5], v12, s83, v[10:11]
	v_lshl_add_u64 v[20:21], s[26:27], 0, v[20:21]
	global_load_dwordx4 v[2:5], v[6:7], off
	s_nop 0
	global_load_dwordx4 v[6:9], v[6:7], off offset:1024
	s_nop 0
	global_load_dwordx4 v[10:13], v[14:15], off
	s_nop 0
	global_load_dwordx4 v[14:17], v[14:15], off offset:1024
	v_lshl_add_u64 v[22:23], v[20:21], 0, s[72:73]
	global_load_dwordx4 v[18:21], v[18:19], off offset:2048
	s_nop 0
	global_load_dword v126, v[22:23], off offset:512
	global_load_dword v127, v[22:23], off offset:528
	s_lshl_b32 s1, s6, 9
	v_lshlrev_b32_e32 v22, 3, v1
	s_add_u32 s1, s75, s1
	v_and_b32_e32 v22, 0xfffffe00, v22
	v_lshlrev_b32_e32 v23, 2, v25
	s_addc_u32 s4, s79, 0
	s_lshl_b32 s3, s3, 2
	v_add3_u32 v22, s82, v22, v23
	s_add_u32 s10, s1, s3
	ds_write2st64_b32 v22, v94, v94 offset1:1
	s_addc_u32 s11, s4, 0
	s_add_u32 s12, s8, s0
	s_addc_u32 s13, s9, 0
	v_mov_b32_e32 v95, v94
	s_add_u32 s14, s26, s72
	s_mov_b32 s17, 0
	v_mov_b64_e32 v[96:97], v[94:95]
	v_mov_b64_e32 v[98:99], v[94:95]
	v_mov_b64_e32 v[100:101], v[94:95]
	s_addc_u32 s15, s27, 0
	v_mov_b64_e32 v[102:103], v[94:95]
	v_mov_b64_e32 v[104:105], v[94:95]
	v_mov_b64_e32 v[106:107], v[94:95]
	v_mov_b64_e32 v[108:109], v[94:95]
	v_mov_b64_e32 v[110:111], v[94:95]
	s_waitcnt vmcnt(8)
	v_mul_f32_e32 v22, 0x3fb8aa3b, v24
	v_exp_f32_e32 v125, v22
	v_mov_b32_e32 v184, 0
	v_mov_b32_e32 v185, 0
	v_mov_b32_e32 v186, 0
	v_mov_b32_e32 v187, 0
	v_mov_b32_e32 v188, 0
	v_mov_b32_e32 v189, 0
	v_mov_b32_e32 v190, 0
	v_mov_b32_e32 v191, 0
	v_mov_b32_e32 v192, 0
	v_mov_b32_e32 v193, 0
	v_mov_b32_e32 v194, 0
	v_mov_b32_e32 v195, 0
	v_mov_b32_e32 v196, 0
	v_mov_b32_e32 v197, 0
	v_mov_b32_e32 v198, 0
	v_mov_b32_e32 v199, 0
	v_mov_b32_e32 v200, 0
	v_mov_b32_e32 v201, 0
	v_mov_b32_e32 v202, 0
	v_mov_b32_e32 v203, 0
	v_mov_b32_e32 v204, 0
	v_mov_b32_e32 v205, 0
	v_mov_b32_e32 v206, 0
	v_mov_b32_e32 v207, 0
	v_mov_b32_e32 v208, 0
	v_mov_b32_e32 v209, 0
	v_mov_b32_e32 v210, 0
	v_mov_b32_e32 v211, 0
	v_mov_b32_e32 v212, 0
	v_mov_b32_e32 v213, 0
	v_mov_b32_e32 v214, 0
	v_mov_b32_e32 v215, 0
	v_mov_b32_e32 v238, 1.0
	v_mov_b32_e32 v182, 0x15800
	ds_write_b32 v182, v184 offset:0
	ds_write_b32 v182, v184 offset:4
	ds_write_b32 v182, v184 offset:8
	ds_write_b32 v182, v184 offset:12
	ds_write_b32 v182, v184 offset:16
	ds_write_b32 v182, v184 offset:20
	ds_write_b32 v182, v184 offset:24
	ds_write_b32 v182, v184 offset:28
	v_and_b32_e32 v166, 15, v180
	v_bfe_u32 v167, v180, 4, 2
	v_lshrrev_b32_e32 v168, 6, v180
	v_lshrrev_b32_e32 v177, 2, v166
	v_and_b32_e32 v178, 1, v166
	v_lshl_add_u32 v177, v178, 2, v177
	v_lshlrev_b32_e32 v173, 5, v177
	v_mul_u32_u24_e32 v177, 0x210, v177
	v_and_b32_e32 v178, 2, v166
	v_lshl_add_u32 v173, v178, 7, v173
	v_lshl_add_u32 v173, v167, 2, v173
	v_add_u32_e32 v173, 0x14800, v173
	v_sub_u32_e32 v178, 2, v178
	v_mul_u32_u24_e32 v178, 0x4200, v178
	v_lshl_add_u32 v169, v167, 4, v177
	v_add_u32_e32 v169, v169, v178
	v_mul_u32_u24_e32 v177, 0x210, v167
	v_lshl_add_u32 v170, v166, 2, v177
	v_add_u32_e32 v170, 0x8400, v170
	v_lshlrev_b32_e32 v177, 6, v168
	v_lshl_add_u32 v177, v166, 2, v177
	v_lshl_add_u32 v177, v167, 8, v177
	v_add_u32_e32 v171, 0x10800, v177
	v_add_u32_e32 v172, 0x1d800, v177
	v_lshlrev_b32_e32 v177, 2, v167
	v_add_u32_e32 v174, 0x21800, v177
	v_add_u32_e32 v176, 0x21a00, v177
	v_mov_b32_e32 v175, 0x21900
	v_mov_b32_e32 v236, 0x15800
	v_mov_b32_e32 v237, 1
	v_mov_b32_e32 v232, 0
	v_mov_b32_e32 v233, 0
	v_and_b32_e32 v150, 15, v180
	v_bfe_u32 v151, v180, 4, 2
	v_lshrrev_b32_e32 v152, 6, v180
	v_and_b32_e32 v231, 7, v150
	v_lshl_add_u32 v153, v152, 3, v231
	v_mul_u32_u24_e32 v153, 0x210, v153
	v_lshl_add_u32 v217, v151, 4, v153
	v_and_b32_e32 v154, 8, v150
	v_sub_u32_e32 v154, 8, v154
	v_mul_u32_u24_e32 v154, 0x1080, v154
	v_add_u32_e32 v216, v217, v154
	v_add_u32_e32 v217, 0x8400, v217
	v_lshrrev_b32_e32 v155, 1, v151
	v_and_b32_e32 v156, 1, v151
	v_lshl_add_u32 v153, v152, 1, v156
	v_lshlrev_b32_e32 v218, 4, v153
	v_add_u32_e32 v219, 0x21900, v218
	v_add_u32_e32 v218, 0x21800, v218
	v_lshl_add_u32 v220, v152, 3, v231
	v_lshlrev_b32_e32 v220, 2, v220
	v_add_u32_e32 v220, 0x21800, v220
	v_lshl_add_u32 v221, v152, 1, v155
	v_lshlrev_b32_e32 v221, 8, v221
	v_lshl_add_u32 v221, v156, 7, v221
	v_lshl_add_u32 v221, v231, 2, v221
	v_add_u32_e32 v221, 0x14800, v221
	v_sub_u32_e32 v154, 1, v155
	v_add_u32_e32 v222, v231, v154
	v_lshlrev_b32_e32 v153, 2, v156
	v_sub_u32_e32 v222, v222, v153
	v_mov_b32_e32 v223, 1.0
	v_lshlrev_b32_e32 v224, 9, v152
	v_add_u32_e32 v224, 0x14800, v224
	v_lshlrev_b32_e32 v225, 5, v152
	v_add_u32_e32 v225, 0x21b00, v225
	v_lshl_add_u32 v226, v231, 2, v224
	v_lshl_add_u32 v227, v151, 6, v224
	v_lshl_add_u32 v228, v231, 2, v227
	v_and_b32_e32 v153, 63, v180
	v_lshlrev_b32_e32 v229, 11, v152
	v_lshl_add_u32 v229, v153, 2, v229
	v_add_u32_e32 v229, 0x10800, v229
	v_lshlrev_b32_e32 v230, 5, v152
	v_add_u32_e32 v230, 0x21800, v230
	s_branch .LBB0_537

.LBB0_539:
	s_or_b64 exec, exec, s[0:1]
	v_bfe_u32 v25, v112, 1, 4
	v_subrev_co_u32_e32 v27, vcc, 10, v25
	s_xor_b64 s[4:5], vcc, -1
	s_waitcnt lgkmcnt(0)
	s_barrier
	ds_read_b128 v[30:33], v216 offset:0
	ds_read_b128 v[62:65], v217 offset:0
	ds_read_b128 v[34:37], v216 offset:64
	ds_read_b128 v[66:69], v217 offset:64
	ds_read_b128 v[38:41], v216 offset:128
	ds_read_b128 v[70:73], v217 offset:128
	ds_read_b128 v[42:45], v216 offset:192
	ds_read_b128 v[74:77], v217 offset:192
	ds_read_b128 v[46:49], v216 offset:256
	ds_read_b128 v[78:81], v217 offset:256
	ds_read_b128 v[50:53], v216 offset:320
	ds_read_b128 v[82:85], v217 offset:320
	ds_read_b128 v[54:57], v216 offset:384
	ds_read_b128 v[86:89], v217 offset:384
	ds_read_b128 v[58:61], v216 offset:448
	ds_read_b128 v[90:93], v217 offset:448
	ds_read_b128 v[140:143], v218
	ds_read_b128 v[144:147], v219
	ds_read_b32 v148, v220
	v_bfe_u32 v155, v180, 5, 1
	v_cmp_ge_i32_e64 s[0:1], 1, v222
	v_cmp_ge_i32_e64 s[4:5], 2, v222
	v_cmp_ge_i32_e64 s[6:7], 3, v222
	v_cmp_eq_u32_e64 s[80:81], 1, v155
	v_cmp_ge_i32_e32 vcc, 0, v222
	s_waitcnt lgkmcnt(0)
	v_mfma_f32_16x16x4_f32 v[96:99], v30, v62, 0
	v_mfma_f32_16x16x4_f32 v[100:103], v31, v63, 0
	v_mfma_f32_16x16x4_f32 v[96:99], v32, v64, v[96:99]
	v_mfma_f32_16x16x4_f32 v[100:103], v33, v65, v[100:103]
	v_sub_f32_e32 v164, v140, v148
	v_sub_f32_e32 v165, v141, v148
	v_sub_f32_e32 v166, v142, v148
	v_sub_f32_e32 v167, v143, v148
	v_min_f32_e32 v164, 0, v164
	v_min_f32_e32 v165, 0, v165
	v_min_f32_e32 v166, 0, v166
	v_min_f32_e32 v167, 0, v167
	v_mul_f32_e32 v164, 0x3fb8aa3b, v164
	v_mul_f32_e32 v165, 0x3fb8aa3b, v165
	v_mul_f32_e32 v166, 0x3fb8aa3b, v166
	v_mul_f32_e32 v167, 0x3fb8aa3b, v167
	v_exp_f32_e32 v164, v164
	v_exp_f32_e32 v165, v165
	v_exp_f32_e32 v166, v166
	v_exp_f32_e32 v167, v167
	v_mfma_f32_16x16x4_f32 v[96:99], v34, v66, v[96:99]
	v_mfma_f32_16x16x4_f32 v[100:103], v35, v67, v[100:103]
	v_mfma_f32_16x16x4_f32 v[96:99], v36, v68, v[96:99]
	v_mfma_f32_16x16x4_f32 v[100:103], v37, v69, v[100:103]
	v_cndmask_b32_e64 v144, v144, v223, s[80:81]
	v_cndmask_b32_e64 v145, v145, v223, s[80:81]
	v_cndmask_b32_e64 v146, v146, v223, s[80:81]
	v_cndmask_b32_e64 v147, v147, v223, s[80:81]
	v_mul_f32_e32 v164, v164, v144
	v_mul_f32_e32 v165, v165, v145
	v_mul_f32_e32 v166, v166, v146
	v_mul_f32_e32 v167, v167, v147
	v_cndmask_b32_e32 v164, 0, v164, vcc
	v_cndmask_b32_e64 v165, 0, v165, s[0:1]
	v_cndmask_b32_e64 v166, 0, v166, s[4:5]
	v_cndmask_b32_e64 v167, 0, v167, s[6:7]
	v_mfma_f32_16x16x4_f32 v[96:99], v38, v70, v[96:99]
	v_mfma_f32_16x16x4_f32 v[100:103], v39, v71, v[100:103]
	v_mfma_f32_16x16x4_f32 v[96:99], v40, v72, v[96:99]
	v_mfma_f32_16x16x4_f32 v[100:103], v41, v73, v[100:103]
	v_mfma_f32_16x16x4_f32 v[96:99], v42, v74, v[96:99]
	v_mfma_f32_16x16x4_f32 v[100:103], v43, v75, v[100:103]
	v_mfma_f32_16x16x4_f32 v[96:99], v44, v76, v[96:99]
	v_mfma_f32_16x16x4_f32 v[100:103], v45, v77, v[100:103]
	v_mfma_f32_16x16x4_f32 v[96:99], v46, v78, v[96:99]
	v_mfma_f32_16x16x4_f32 v[100:103], v47, v79, v[100:103]
	v_mfma_f32_16x16x4_f32 v[96:99], v48, v80, v[96:99]
	v_mfma_f32_16x16x4_f32 v[100:103], v49, v81, v[100:103]
	v_mfma_f32_16x16x4_f32 v[96:99], v50, v82, v[96:99]
	v_mfma_f32_16x16x4_f32 v[100:103], v51, v83, v[100:103]
	v_mfma_f32_16x16x4_f32 v[96:99], v52, v84, v[96:99]
	v_mfma_f32_16x16x4_f32 v[100:103], v53, v85, v[100:103]
	v_mfma_f32_16x16x4_f32 v[96:99], v54, v86, v[96:99]
	v_mfma_f32_16x16x4_f32 v[100:103], v55, v87, v[100:103]
	v_mfma_f32_16x16x4_f32 v[96:99], v56, v88, v[96:99]
	v_mfma_f32_16x16x4_f32 v[100:103], v57, v89, v[100:103]
	v_mfma_f32_16x16x4_f32 v[96:99], v58, v90, v[96:99]
	v_mfma_f32_16x16x4_f32 v[100:103], v59, v91, v[100:103]
	v_mfma_f32_16x16x4_f32 v[96:99], v60, v92, v[96:99]
	v_mfma_f32_16x16x4_f32 v[100:103], v61, v93, v[100:103]
	s_nop 7
	s_nop 2
	v_pk_add_f32 v[96:97], v[96:97], v[100:101]
	v_pk_add_f32 v[98:99], v[98:99], v[102:103]
	v_mul_f32_e32 v96, v96, v164
	v_mul_f32_e32 v97, v97, v165
	v_mul_f32_e32 v98, v98, v166
	v_mul_f32_e32 v99, v99, v167
	ds_write_b32 v221, v96 offset:0
	ds_write_b32 v221, v97 offset:32
	ds_write_b32 v221, v98 offset:64
	ds_write_b32 v221, v99 offset:96
	ds_read_b128 v[30:33], v224 offset:32
	ds_read_b128 v[34:37], v224 offset:64
	ds_read_b128 v[38:41], v224 offset:96
	ds_read_b128 v[42:45], v224 offset:128
	ds_read_b128 v[50:53], v224 offset:160
	ds_read_b128 v[54:57], v224 offset:176
	ds_read_b128 v[58:61], v224 offset:192
	ds_read_b128 v[62:65], v224 offset:208
	ds_read_b128 v[66:69], v224 offset:224
	ds_read_b128 v[70:73], v224 offset:240
	ds_read_b128 v[74:77], v227 offset:256
	ds_read_b128 v[78:81], v227 offset:272
	ds_read_b128 v[82:85], v227 offset:288
	ds_read_b128 v[86:89], v227 offset:304
	ds_read_b128 v[104:107], v225
	ds_read_b128 v[108:111], v225 offset:16
	v_cmp_eq_u32_e32 vcc, 0, v231
	v_cndmask_b32_e32 v96, 0, v223, vcc
	v_cmp_eq_u32_e32 vcc, 1, v231
	v_cndmask_b32_e32 v97, 0, v223, vcc
	v_cmp_eq_u32_e32 vcc, 2, v231
	v_cndmask_b32_e32 v98, 0, v223, vcc
	v_cmp_eq_u32_e32 vcc, 3, v231
	v_cndmask_b32_e32 v99, 0, v223, vcc
	v_cmp_eq_u32_e32 vcc, 4, v231
	v_cndmask_b32_e32 v100, 0, v223, vcc
	v_cmp_eq_u32_e32 vcc, 5, v231
	v_cndmask_b32_e32 v101, 0, v223, vcc
	v_cmp_eq_u32_e32 vcc, 6, v231
	v_cndmask_b32_e32 v102, 0, v223, vcc
	v_cmp_eq_u32_e32 vcc, 7, v231
	v_cndmask_b32_e32 v103, 0, v223, vcc
	s_waitcnt lgkmcnt(0)
	v_fma_f32 v97, -v30, v96, v97
	v_fma_f32 v98, -v34, v96, v98
	v_fma_f32 v99, -v38, v96, v99
	v_fma_f32 v100, -v42, v96, v100
	v_fma_f32 v101, -v50, v96, v101
	v_fma_f32 v102, -v58, v96, v102
	v_fma_f32 v103, -v66, v96, v103
	v_fma_f32 v98, -v35, v97, v98
	v_fma_f32 v99, -v39, v97, v99
	v_fma_f32 v100, -v43, v97, v100
	v_fma_f32 v101, -v51, v97, v101
	v_fma_f32 v102, -v59, v97, v102
	v_fma_f32 v103, -v67, v97, v103
	v_fma_f32 v99, -v40, v98, v99
	v_fma_f32 v100, -v44, v98, v100
	v_fma_f32 v101, -v52, v98, v101
	v_fma_f32 v102, -v60, v98, v102
	v_fma_f32 v103, -v68, v98, v103
	v_fma_f32 v100, -v45, v99, v100
	v_fma_f32 v101, -v53, v99, v101
	v_fma_f32 v102, -v61, v99, v102
	v_fma_f32 v103, -v69, v99, v103
	v_fma_f32 v101, -v54, v100, v101
	v_fma_f32 v102, -v62, v100, v102
	v_fma_f32 v103, -v70, v100, v103
	v_fma_f32 v102, -v63, v101, v102
	v_fma_f32 v103, -v71, v101, v103
	v_fma_f32 v103, -v72, v102, v103
	v_mul_f32_e32 v114, v74, v96
	v_fmac_f32_e32 v114, v75, v97
	v_fmac_f32_e32 v114, v76, v98
	v_fmac_f32_e32 v114, v77, v99
	v_fmac_f32_e32 v114, v78, v100
	v_fmac_f32_e32 v114, v79, v101
	v_fmac_f32_e32 v114, v80, v102
	v_fmac_f32_e32 v114, v81, v103
	v_mul_f32_e32 v115, v82, v96
	v_fmac_f32_e32 v115, v83, v97
	v_fmac_f32_e32 v115, v84, v98
	v_fmac_f32_e32 v115, v85, v99
	v_fmac_f32_e32 v115, v86, v100
	v_fmac_f32_e32 v115, v87, v101
	v_fmac_f32_e32 v115, v88, v102
	v_fmac_f32_e32 v115, v89, v103
	v_mul_f32_e32 v104, v104, v96
	v_mul_f32_e32 v105, v105, v97
	v_mul_f32_e32 v106, v106, v98
	v_mul_f32_e32 v107, v107, v99
	v_mul_f32_e32 v108, v108, v100
	v_mul_f32_e32 v109, v109, v101
	v_mul_f32_e32 v110, v110, v102
	v_mul_f32_e32 v111, v111, v103
	ds_write_b32 v226, v104 offset:0
	ds_write_b32 v226, v105 offset:32
	ds_write_b32 v226, v106 offset:64
	ds_write_b32 v226, v107 offset:96
	ds_write_b32 v226, v108 offset:128
	ds_write_b32 v226, v109 offset:160
	ds_write_b32 v226, v110 offset:192
	ds_write_b32 v226, v111 offset:224
	ds_write_b32 v228, v114 offset:256
	ds_write_b32 v228, v115 offset:288
	ds_read_b32 v30, v229 offset:0
	ds_read_b32 v31, v229 offset:256
	ds_read_b32 v32, v229 offset:512
	ds_read_b32 v33, v229 offset:768
	ds_read_b32 v34, v229 offset:1024
	ds_read_b32 v35, v229 offset:1280
	ds_read_b32 v36, v229 offset:1536
	ds_read_b32 v37, v229 offset:1792
	ds_read_b128 v[40:43], v230 offset:256
	ds_read_b128 v[44:47], v230 offset:272
	ds_read_b128 v[48:51], v230 offset:512
	ds_read_b128 v[52:55], v230 offset:528
	s_waitcnt lgkmcnt(0)
	v_mul_f32_e32 v30, v40, v30
	v_mul_f32_e32 v31, v41, v31
	v_mul_f32_e32 v32, v42, v32
	v_mul_f32_e32 v33, v43, v33
	v_mul_f32_e32 v34, v44, v34
	v_mul_f32_e32 v35, v45, v35
	v_mul_f32_e32 v36, v46, v36
	v_mul_f32_e32 v37, v47, v37
	v_mul_f32_e64 v48, -v40, v48
	v_mul_f32_e64 v49, -v41, v49
	v_mul_f32_e64 v50, -v42, v50
	v_mul_f32_e64 v51, -v43, v51
	v_mul_f32_e64 v52, -v44, v52
	v_mul_f32_e64 v53, -v45, v53
	v_mul_f32_e64 v54, -v46, v54
	v_mul_f32_e64 v55, -v47, v55
	ds_write_b32 v229, v30 offset:0
	ds_write_b32 v229, v31 offset:256
	ds_write_b32 v229, v32 offset:512
	ds_write_b32 v229, v33 offset:768
	ds_write_b32 v229, v34 offset:1024
	ds_write_b32 v229, v35 offset:1280
	ds_write_b32 v229, v36 offset:1536
	ds_write_b32 v229, v37 offset:1792
	ds_write_b128 v230, v[48:51]
	ds_write_b128 v230, v[52:55] offset:16
	s_lshl_b32 s0, s17, 6
	s_add_i32 s72, s0, s16
	v_and_b32_e32 v128, 63, v112
	s_cmp_eq_u32 s17, 31
	s_waitcnt lgkmcnt(0)
	s_barrier
	s_cbranch_scc1 .LBB0_549
	s_add_i32 s0, s72, 64
	s_mov_b32 s1, s73
	v_ashrrev_i32_e32 v27, 31, v26
	v_lshlrev_b32_e32 v2, 1, v23
	v_mov_b32_e32 v3, v94
	v_ashrrev_i32_e32 v23, 31, v22
	v_ashrrev_i32_e32 v25, 31, v24
	v_lshl_add_u64 v[18:19], s[0:1], 0, v[26:27]
	v_mov_b64_e32 v[20:21], s[12:13]
	v_lshl_add_u64 v[10:11], s[8:9], 0, v[2:3]
	v_lshl_add_u64 v[2:3], s[0:1], 0, v[22:23]
	v_lshl_add_u64 v[12:13], s[0:1], 0, v[24:25]
	v_mad_u64_u32 v[20:21], s[4:5], v18, s83, v[20:21]
	v_mad_u64_u32 v[6:7], s[4:5], v2, s83, v[10:11]
	v_mad_u64_u32 v[14:15], s[4:5], v12, s83, v[10:11]
	v_mad_i32_i24 v21, v19, s83, v21
	v_lshlrev_b32_e32 v18, 1, v28
	v_mov_b32_e32 v19, v94
	v_mad_i32_i24 v7, v3, s83, v7
	v_mad_i32_i24 v15, v13, s83, v15
	v_lshl_add_u64 v[18:19], v[20:21], 0, v[18:19]
	v_or_b32_e32 v22, s0, v128
	v_mov_b64_e32 v[20:21], s[14:15]
	global_load_dwordx4 v[2:5], v[6:7], off
	s_nop 0
	global_load_dwordx4 v[6:9], v[6:7], off offset:1024
	s_nop 0
	global_load_dwordx4 v[10:13], v[14:15], off
	s_nop 0
	global_load_dwordx4 v[14:17], v[14:15], off offset:1024
	v_mad_u64_u32 v[22:23], s[0:1], v22, s87, v[20:21]
	global_load_dwordx4 v[18:21], v[18:19], off offset:2048
	s_nop 0
	global_load_dword v126, v[22:23], off offset:512
	global_load_dword v127, v[22:23], off offset:528
.LBB0_549:
	v_readfirstlane_b32 s0, v180
	s_nop 1
	s_cmpk_ge_u32 s0, 0x100
	s_cbranch_scc1 .Lgdn_out
	s_mov_b32 s40, 1
	s_mov_b32 s41, 0
	ds_read_b128 v[22:25], v169 offset:0
	ds_read_b128 v[26:29], v169 offset:64
	ds_read_b128 v[30:33], v169 offset:128
	ds_read_b128 v[34:37], v169 offset:192
	ds_read_b128 v[38:41], v169 offset:256
	ds_read_b128 v[42:45], v169 offset:320
	ds_read_b128 v[46:49], v169 offset:384
	ds_read_b128 v[50:53], v169 offset:448
	s_waitcnt lgkmcnt(0)
	v_mfma_f32_16x16x4_f32 v[96:99], v22, v184, 0
	v_mfma_f32_16x16x4_f32 v[100:103], v23, v185, 0
	v_mfma_f32_16x16x4_f32 v[96:99], v24, v186, v[96:99]
	v_mfma_f32_16x16x4_f32 v[100:103], v25, v187, v[100:103]
	ds_read_b32 v54, v170 offset:0
	ds_read_b32 v55, v170 offset:64
	ds_read_b32 v56, v170 offset:128
	ds_read_b32 v57, v170 offset:192
	v_mfma_f32_16x16x4_f32 v[96:99], v26, v188, v[96:99]
	v_mfma_f32_16x16x4_f32 v[100:103], v27, v189, v[100:103]
	v_mfma_f32_16x16x4_f32 v[96:99], v28, v190, v[96:99]
	v_mfma_f32_16x16x4_f32 v[100:103], v29, v191, v[100:103]
	ds_read_b128 v[22:25], v169 offset:4224
	ds_read_b32 v58, v170 offset:256
	ds_read_b32 v59, v170 offset:320
	ds_read_b32 v60, v170 offset:384
	ds_read_b32 v61, v170 offset:448
	v_mfma_f32_16x16x4_f32 v[96:99], v30, v192, v[96:99]
	v_mfma_f32_16x16x4_f32 v[100:103], v31, v193, v[100:103]
	v_mfma_f32_16x16x4_f32 v[96:99], v32, v194, v[96:99]
	v_mfma_f32_16x16x4_f32 v[100:103], v33, v195, v[100:103]
	ds_read_b128 v[26:29], v169 offset:4288
	ds_read_b32 v62, v170 offset:2112
	ds_read_b32 v63, v170 offset:2176
	ds_read_b32 v64, v170 offset:2240
	ds_read_b32 v65, v170 offset:2304
	v_mfma_f32_16x16x4_f32 v[96:99], v34, v196, v[96:99]
	v_mfma_f32_16x16x4_f32 v[100:103], v35, v197, v[100:103]
	v_mfma_f32_16x16x4_f32 v[96:99], v36, v198, v[96:99]
	v_mfma_f32_16x16x4_f32 v[100:103], v37, v199, v[100:103]
	ds_read_b128 v[30:33], v169 offset:4352
	ds_read_b32 v66, v170 offset:2368
	ds_read_b32 v67, v170 offset:2432
	ds_read_b32 v68, v170 offset:2496
	ds_read_b32 v69, v170 offset:2560
	v_mfma_f32_16x16x4_f32 v[96:99], v38, v200, v[96:99]
	v_mfma_f32_16x16x4_f32 v[100:103], v39, v201, v[100:103]
	v_mfma_f32_16x16x4_f32 v[96:99], v40, v202, v[96:99]
	v_mfma_f32_16x16x4_f32 v[100:103], v41, v203, v[100:103]
	ds_read_b128 v[34:37], v169 offset:4416
	ds_read_b32 v95, v175 offset:284
	ds_read2_b32 v[72:73], v174 offset0:0 offset1:4
	ds_read2_b32 v[74:75], v176 offset0:0 offset1:4
	ds_read2st64_b32 v[70:71], v171 offset0:0 offset1:4
	ds_read_b32 v93, v173 offset:0
	ds_read_b32 v90, v173 offset:16
	v_mfma_f32_16x16x4_f32 v[96:99], v42, v204, v[96:99]
	v_mfma_f32_16x16x4_f32 v[100:103], v43, v205, v[100:103]
	v_mfma_f32_16x16x4_f32 v[96:99], v44, v206, v[96:99]
	v_mfma_f32_16x16x4_f32 v[100:103], v45, v207, v[100:103]
	ds_read_b128 v[38:41], v169 offset:4480
	v_mfma_f32_16x16x4_f32 v[96:99], v46, v208, v[96:99]
	v_mfma_f32_16x16x4_f32 v[100:103], v47, v209, v[100:103]
	v_mfma_f32_16x16x4_f32 v[96:99], v48, v210, v[96:99]
	v_mfma_f32_16x16x4_f32 v[100:103], v49, v211, v[100:103]
	ds_read_b128 v[42:45], v169 offset:4544
	v_mfma_f32_16x16x4_f32 v[96:99], v50, v212, v[96:99]
	v_mfma_f32_16x16x4_f32 v[100:103], v51, v213, v[100:103]
	v_mfma_f32_16x16x4_f32 v[96:99], v52, v214, v[96:99]
	v_mfma_f32_16x16x4_f32 v[100:103], v53, v215, v[100:103]
	ds_read_b128 v[46:49], v169 offset:4608
	ds_read_b128 v[50:53], v169 offset:4672
	s_waitcnt lgkmcnt(4)
	v_mul_f32_e32 v240, v238, v95
	v_pk_mul_f32 v[76:77], v[72:73], v[238:239] op_sel_hi:[1,0]
	v_pk_mul_f32 v[78:79], v[74:75], v[238:239] op_sel_hi:[1,0]
	v_rcp_f32_e32 v88, v240
	v_readfirstlane_b32 s0, v240
	s_nop 3
	v_pk_add_f32 v[96:97], v[96:97], v[100:101]
	v_pk_add_f32 v[98:99], v[98:99], v[102:103]
	v_pk_fma_f32 v[80:81], v[76:77], v[96:97], v[70:71]
	v_pk_mul_f32 v[234:235], v[78:79], v[98:99]
	s_nop 1
	v_mfma_f32_16x16x4_f32 v[82:85], v93, v80, v[232:235]
	v_mfma_f32_16x16x4_f32 v[82:85], v90, v81, v[82:85]
	s_cmp_lt_u32 s0, 0x2b800000
	s_cbranch_scc0 .Lgdn_nomat_0
	v_pk_mul_f32 v[184:185], v[184:185], v[240:241] op_sel_hi:[1,0]
	v_pk_mul_f32 v[186:187], v[186:187], v[240:241] op_sel_hi:[1,0]
	v_pk_mul_f32 v[188:189], v[188:189], v[240:241] op_sel_hi:[1,0]
	v_pk_mul_f32 v[190:191], v[190:191], v[240:241] op_sel_hi:[1,0]
	v_pk_mul_f32 v[192:193], v[192:193], v[240:241] op_sel_hi:[1,0]
	v_pk_mul_f32 v[194:195], v[194:195], v[240:241] op_sel_hi:[1,0]
	v_pk_mul_f32 v[196:197], v[196:197], v[240:241] op_sel_hi:[1,0]
	v_pk_mul_f32 v[198:199], v[198:199], v[240:241] op_sel_hi:[1,0]
	v_pk_mul_f32 v[200:201], v[200:201], v[240:241] op_sel_hi:[1,0]
	v_pk_mul_f32 v[202:203], v[202:203], v[240:241] op_sel_hi:[1,0]
	v_pk_mul_f32 v[204:205], v[204:205], v[240:241] op_sel_hi:[1,0]
	v_pk_mul_f32 v[206:207], v[206:207], v[240:241] op_sel_hi:[1,0]
	v_pk_mul_f32 v[208:209], v[208:209], v[240:241] op_sel_hi:[1,0]
	v_pk_mul_f32 v[210:211], v[210:211], v[240:241] op_sel_hi:[1,0]
	v_pk_mul_f32 v[212:213], v[212:213], v[240:241] op_sel_hi:[1,0]
	v_pk_mul_f32 v[214:215], v[214:215], v[240:241] op_sel_hi:[1,0]
	v_mov_b32_e32 v240, 1.0
	v_mov_b32_e32 v88, 1.0
.Lgdn_nomat_0:
	v_mov_b32_e32 v238, v240
	s_nop 7
	v_pk_mul_f32 v[86:87], v[82:83], v[88:89] op_sel_hi:[1,0]
	s_nop 1
	v_mfma_f32_16x16x4_f32 v[184:187], v54, v86, v[184:187]
	v_mfma_f32_16x16x4_f32 v[188:191], v55, v86, v[188:191]
	v_mfma_f32_16x16x4_f32 v[192:195], v56, v86, v[192:195]
	v_mfma_f32_16x16x4_f32 v[196:199], v57, v86, v[196:199]
	v_mfma_f32_16x16x4_f32 v[200:203], v58, v86, v[200:203]
	v_mfma_f32_16x16x4_f32 v[204:207], v59, v86, v[204:207]
	v_mfma_f32_16x16x4_f32 v[208:211], v60, v86, v[208:211]
	v_mfma_f32_16x16x4_f32 v[212:215], v61, v86, v[212:215]
	v_mfma_f32_16x16x4_f32 v[184:187], v62, v87, v[184:187]
	v_mfma_f32_16x16x4_f32 v[188:191], v63, v87, v[188:191]
	v_mfma_f32_16x16x4_f32 v[192:195], v64, v87, v[192:195]
	v_mfma_f32_16x16x4_f32 v[196:199], v65, v87, v[196:199]
	v_mfma_f32_16x16x4_f32 v[200:203], v66, v87, v[200:203]
	v_mfma_f32_16x16x4_f32 v[204:207], v67, v87, v[204:207]
	v_mfma_f32_16x16x4_f32 v[208:211], v68, v87, v[208:211]
	v_mfma_f32_16x16x4_f32 v[212:215], v69, v87, v[212:215]
	ds_write2st64_b32 v172, v84, v85 offset0:0 offset1:4
	s_mov_b64 exec, s[40:41]
	ds_add_u32 v236, v237 offset:0
	s_mov_b64 exec, -1
	s_waitcnt lgkmcnt(2)
	v_mfma_f32_16x16x4_f32 v[96:99], v22, v184, 0
	v_mfma_f32_16x16x4_f32 v[100:103], v23, v185, 0
	v_mfma_f32_16x16x4_f32 v[96:99], v24, v186, v[96:99]
	v_mfma_f32_16x16x4_f32 v[100:103], v25, v187, v[100:103]
	ds_read_b32 v54, v170 offset:4224
	ds_read_b32 v55, v170 offset:4288
	ds_read_b32 v56, v170 offset:4352
	ds_read_b32 v57, v170 offset:4416
	v_mfma_f32_16x16x4_f32 v[96:99], v26, v188, v[96:99]
	v_mfma_f32_16x16x4_f32 v[100:103], v27, v189, v[100:103]
	v_mfma_f32_16x16x4_f32 v[96:99], v28, v190, v[96:99]
	v_mfma_f32_16x16x4_f32 v[100:103], v29, v191, v[100:103]
	ds_read_b128 v[22:25], v169 offset:8448
	ds_read_b32 v58, v170 offset:4480
	ds_read_b32 v59, v170 offset:4544
	ds_read_b32 v60, v170 offset:4608
	ds_read_b32 v61, v170 offset:4672
	v_mfma_f32_16x16x4_f32 v[96:99], v30, v192, v[96:99]
	v_mfma_f32_16x16x4_f32 v[100:103], v31, v193, v[100:103]
	v_mfma_f32_16x16x4_f32 v[96:99], v32, v194, v[96:99]
	v_mfma_f32_16x16x4_f32 v[100:103], v33, v195, v[100:103]
	ds_read_b128 v[26:29], v169 offset:8512
	ds_read_b32 v62, v170 offset:6336
	ds_read_b32 v63, v170 offset:6400
	ds_read_b32 v64, v170 offset:6464
	ds_read_b32 v65, v170 offset:6528
	v_mfma_f32_16x16x4_f32 v[96:99], v34, v196, v[96:99]
	v_mfma_f32_16x16x4_f32 v[100:103], v35, v197, v[100:103]
	v_mfma_f32_16x16x4_f32 v[96:99], v36, v198, v[96:99]
	v_mfma_f32_16x16x4_f32 v[100:103], v37, v199, v[100:103]
	ds_read_b128 v[30:33], v169 offset:8576
	ds_read_b32 v66, v170 offset:6592
	ds_read_b32 v67, v170 offset:6656
	ds_read_b32 v68, v170 offset:6720
	ds_read_b32 v69, v170 offset:6784
	v_mfma_f32_16x16x4_f32 v[96:99], v38, v200, v[96:99]
	v_mfma_f32_16x16x4_f32 v[100:103], v39, v201, v[100:103]
	v_mfma_f32_16x16x4_f32 v[96:99], v40, v202, v[96:99]
	v_mfma_f32_16x16x4_f32 v[100:103], v41, v203, v[100:103]
	ds_read_b128 v[34:37], v169 offset:8640
	ds_read_b32 v95, v175 offset:316
	ds_read2_b32 v[72:73], v174 offset0:8 offset1:12
	ds_read2_b32 v[74:75], v176 offset0:8 offset1:12
	ds_read2st64_b32 v[70:71], v171 offset0:8 offset1:12
	ds_read_b32 v93, v173 offset:512
	ds_read_b32 v90, v173 offset:528
	v_mfma_f32_16x16x4_f32 v[96:99], v42, v204, v[96:99]
	v_mfma_f32_16x16x4_f32 v[100:103], v43, v205, v[100:103]
	v_mfma_f32_16x16x4_f32 v[96:99], v44, v206, v[96:99]
	v_mfma_f32_16x16x4_f32 v[100:103], v45, v207, v[100:103]
	ds_read_b128 v[38:41], v169 offset:8704
	v_mfma_f32_16x16x4_f32 v[96:99], v46, v208, v[96:99]
	v_mfma_f32_16x16x4_f32 v[100:103], v47, v209, v[100:103]
	v_mfma_f32_16x16x4_f32 v[96:99], v48, v210, v[96:99]
	v_mfma_f32_16x16x4_f32 v[100:103], v49, v211, v[100:103]
	ds_read_b128 v[42:45], v169 offset:8768
	v_mfma_f32_16x16x4_f32 v[96:99], v50, v212, v[96:99]
	v_mfma_f32_16x16x4_f32 v[100:103], v51, v213, v[100:103]
	v_mfma_f32_16x16x4_f32 v[96:99], v52, v214, v[96:99]
	v_mfma_f32_16x16x4_f32 v[100:103], v53, v215, v[100:103]
	ds_read_b128 v[46:49], v169 offset:8832
	ds_read_b128 v[50:53], v169 offset:8896
	s_waitcnt lgkmcnt(4)
	v_mul_f32_e32 v240, v238, v95
	v_pk_mul_f32 v[76:77], v[72:73], v[238:239] op_sel_hi:[1,0]
	v_pk_mul_f32 v[78:79], v[74:75], v[238:239] op_sel_hi:[1,0]
	v_rcp_f32_e32 v88, v240
	v_readfirstlane_b32 s0, v240
	s_nop 3
	v_pk_add_f32 v[96:97], v[96:97], v[100:101]
	v_pk_add_f32 v[98:99], v[98:99], v[102:103]
	v_pk_fma_f32 v[80:81], v[76:77], v[96:97], v[70:71]
	v_pk_mul_f32 v[234:235], v[78:79], v[98:99]
	s_nop 1
	v_mfma_f32_16x16x4_f32 v[82:85], v93, v80, v[232:235]
	v_mfma_f32_16x16x4_f32 v[82:85], v90, v81, v[82:85]
	s_cmp_lt_u32 s0, 0x2b800000
	s_cbranch_scc0 .Lgdn_nomat_1
	v_pk_mul_f32 v[184:185], v[184:185], v[240:241] op_sel_hi:[1,0]
	v_pk_mul_f32 v[186:187], v[186:187], v[240:241] op_sel_hi:[1,0]
	v_pk_mul_f32 v[188:189], v[188:189], v[240:241] op_sel_hi:[1,0]
	v_pk_mul_f32 v[190:191], v[190:191], v[240:241] op_sel_hi:[1,0]
	v_pk_mul_f32 v[192:193], v[192:193], v[240:241] op_sel_hi:[1,0]
	v_pk_mul_f32 v[194:195], v[194:195], v[240:241] op_sel_hi:[1,0]
	v_pk_mul_f32 v[196:197], v[196:197], v[240:241] op_sel_hi:[1,0]
	v_pk_mul_f32 v[198:199], v[198:199], v[240:241] op_sel_hi:[1,0]
	v_pk_mul_f32 v[200:201], v[200:201], v[240:241] op_sel_hi:[1,0]
	v_pk_mul_f32 v[202:203], v[202:203], v[240:241] op_sel_hi:[1,0]
	v_pk_mul_f32 v[204:205], v[204:205], v[240:241] op_sel_hi:[1,0]
	v_pk_mul_f32 v[206:207], v[206:207], v[240:241] op_sel_hi:[1,0]
	v_pk_mul_f32 v[208:209], v[208:209], v[240:241] op_sel_hi:[1,0]
	v_pk_mul_f32 v[210:211], v[210:211], v[240:241] op_sel_hi:[1,0]
	v_pk_mul_f32 v[212:213], v[212:213], v[240:241] op_sel_hi:[1,0]
	v_pk_mul_f32 v[214:215], v[214:215], v[240:241] op_sel_hi:[1,0]
	v_mov_b32_e32 v240, 1.0
	v_mov_b32_e32 v88, 1.0
.Lgdn_nomat_1:
	v_mov_b32_e32 v238, v240
	s_nop 7
	v_pk_mul_f32 v[86:87], v[82:83], v[88:89] op_sel_hi:[1,0]
	s_nop 1
	v_mfma_f32_16x16x4_f32 v[184:187], v54, v86, v[184:187]
	v_mfma_f32_16x16x4_f32 v[188:191], v55, v86, v[188:191]
	v_mfma_f32_16x16x4_f32 v[192:195], v56, v86, v[192:195]
	v_mfma_f32_16x16x4_f32 v[196:199], v57, v86, v[196:199]
	v_mfma_f32_16x16x4_f32 v[200:203], v58, v86, v[200:203]
	v_mfma_f32_16x16x4_f32 v[204:207], v59, v86, v[204:207]
	v_mfma_f32_16x16x4_f32 v[208:211], v60, v86, v[208:211]
	v_mfma_f32_16x16x4_f32 v[212:215], v61, v86, v[212:215]
	v_mfma_f32_16x16x4_f32 v[184:187], v62, v87, v[184:187]
	v_mfma_f32_16x16x4_f32 v[188:191], v63, v87, v[188:191]
	v_mfma_f32_16x16x4_f32 v[192:195], v64, v87, v[192:195]
	v_mfma_f32_16x16x4_f32 v[196:199], v65, v87, v[196:199]
	v_mfma_f32_16x16x4_f32 v[200:203], v66, v87, v[200:203]
	v_mfma_f32_16x16x4_f32 v[204:207], v67, v87, v[204:207]
	v_mfma_f32_16x16x4_f32 v[208:211], v68, v87, v[208:211]
	v_mfma_f32_16x16x4_f32 v[212:215], v69, v87, v[212:215]
	ds_write2st64_b32 v172, v84, v85 offset0:8 offset1:12
	s_mov_b64 exec, s[40:41]
	ds_add_u32 v236, v237 offset:4
	s_mov_b64 exec, -1
	s_waitcnt lgkmcnt(2)
	v_mfma_f32_16x16x4_f32 v[96:99], v22, v184, 0
	v_mfma_f32_16x16x4_f32 v[100:103], v23, v185, 0
	v_mfma_f32_16x16x4_f32 v[96:99], v24, v186, v[96:99]
	v_mfma_f32_16x16x4_f32 v[100:103], v25, v187, v[100:103]
	ds_read_b32 v54, v170 offset:8448
	ds_read_b32 v55, v170 offset:8512
	ds_read_b32 v56, v170 offset:8576
	ds_read_b32 v57, v170 offset:8640
	v_mfma_f32_16x16x4_f32 v[96:99], v26, v188, v[96:99]
	v_mfma_f32_16x16x4_f32 v[100:103], v27, v189, v[100:103]
	v_mfma_f32_16x16x4_f32 v[96:99], v28, v190, v[96:99]
	v_mfma_f32_16x16x4_f32 v[100:103], v29, v191, v[100:103]
	ds_read_b128 v[22:25], v169 offset:12672
	ds_read_b32 v58, v170 offset:8704
	ds_read_b32 v59, v170 offset:8768
	ds_read_b32 v60, v170 offset:8832
	ds_read_b32 v61, v170 offset:8896
	v_mfma_f32_16x16x4_f32 v[96:99], v30, v192, v[96:99]
	v_mfma_f32_16x16x4_f32 v[100:103], v31, v193, v[100:103]
	v_mfma_f32_16x16x4_f32 v[96:99], v32, v194, v[96:99]
	v_mfma_f32_16x16x4_f32 v[100:103], v33, v195, v[100:103]
	ds_read_b128 v[26:29], v169 offset:12736
	ds_read_b32 v62, v170 offset:10560
	ds_read_b32 v63, v170 offset:10624
	ds_read_b32 v64, v170 offset:10688
	ds_read_b32 v65, v170 offset:10752
	v_mfma_f32_16x16x4_f32 v[96:99], v34, v196, v[96:99]
	v_mfma_f32_16x16x4_f32 v[100:103], v35, v197, v[100:103]
	v_mfma_f32_16x16x4_f32 v[96:99], v36, v198, v[96:99]
	v_mfma_f32_16x16x4_f32 v[100:103], v37, v199, v[100:103]
	ds_read_b128 v[30:33], v169 offset:12800
	ds_read_b32 v66, v170 offset:10816
	ds_read_b32 v67, v170 offset:10880
	ds_read_b32 v68, v170 offset:10944
	ds_read_b32 v69, v170 offset:11008
	v_mfma_f32_16x16x4_f32 v[96:99], v38, v200, v[96:99]
	v_mfma_f32_16x16x4_f32 v[100:103], v39, v201, v[100:103]
	v_mfma_f32_16x16x4_f32 v[96:99], v40, v202, v[96:99]
	v_mfma_f32_16x16x4_f32 v[100:103], v41, v203, v[100:103]
	ds_read_b128 v[34:37], v169 offset:12864
	ds_read_b32 v95, v175 offset:348
	ds_read2_b32 v[72:73], v174 offset0:16 offset1:20
	ds_read2_b32 v[74:75], v176 offset0:16 offset1:20
	ds_read2st64_b32 v[70:71], v171 offset0:16 offset1:20
	ds_read_b32 v93, v173 offset:1024
	ds_read_b32 v90, v173 offset:1040
	v_mfma_f32_16x16x4_f32 v[96:99], v42, v204, v[96:99]
	v_mfma_f32_16x16x4_f32 v[100:103], v43, v205, v[100:103]
	v_mfma_f32_16x16x4_f32 v[96:99], v44, v206, v[96:99]
	v_mfma_f32_16x16x4_f32 v[100:103], v45, v207, v[100:103]
	ds_read_b128 v[38:41], v169 offset:12928
	v_mfma_f32_16x16x4_f32 v[96:99], v46, v208, v[96:99]
	v_mfma_f32_16x16x4_f32 v[100:103], v47, v209, v[100:103]
	v_mfma_f32_16x16x4_f32 v[96:99], v48, v210, v[96:99]
	v_mfma_f32_16x16x4_f32 v[100:103], v49, v211, v[100:103]
	ds_read_b128 v[42:45], v169 offset:12992
	v_mfma_f32_16x16x4_f32 v[96:99], v50, v212, v[96:99]
	v_mfma_f32_16x16x4_f32 v[100:103], v51, v213, v[100:103]
	v_mfma_f32_16x16x4_f32 v[96:99], v52, v214, v[96:99]
	v_mfma_f32_16x16x4_f32 v[100:103], v53, v215, v[100:103]
	ds_read_b128 v[46:49], v169 offset:13056
	ds_read_b128 v[50:53], v169 offset:13120
	s_waitcnt lgkmcnt(4)
	v_mul_f32_e32 v240, v238, v95
	v_pk_mul_f32 v[76:77], v[72:73], v[238:239] op_sel_hi:[1,0]
	v_pk_mul_f32 v[78:79], v[74:75], v[238:239] op_sel_hi:[1,0]
	v_rcp_f32_e32 v88, v240
	v_readfirstlane_b32 s0, v240
	s_nop 3
	v_pk_add_f32 v[96:97], v[96:97], v[100:101]
	v_pk_add_f32 v[98:99], v[98:99], v[102:103]
	v_pk_fma_f32 v[80:81], v[76:77], v[96:97], v[70:71]
	v_pk_mul_f32 v[234:235], v[78:79], v[98:99]
	s_nop 1
	v_mfma_f32_16x16x4_f32 v[82:85], v93, v80, v[232:235]
	v_mfma_f32_16x16x4_f32 v[82:85], v90, v81, v[82:85]
	s_cmp_lt_u32 s0, 0x2b800000
	s_cbranch_scc0 .Lgdn_nomat_2
	v_pk_mul_f32 v[184:185], v[184:185], v[240:241] op_sel_hi:[1,0]
	v_pk_mul_f32 v[186:187], v[186:187], v[240:241] op_sel_hi:[1,0]
	v_pk_mul_f32 v[188:189], v[188:189], v[240:241] op_sel_hi:[1,0]
	v_pk_mul_f32 v[190:191], v[190:191], v[240:241] op_sel_hi:[1,0]
	v_pk_mul_f32 v[192:193], v[192:193], v[240:241] op_sel_hi:[1,0]
	v_pk_mul_f32 v[194:195], v[194:195], v[240:241] op_sel_hi:[1,0]
	v_pk_mul_f32 v[196:197], v[196:197], v[240:241] op_sel_hi:[1,0]
	v_pk_mul_f32 v[198:199], v[198:199], v[240:241] op_sel_hi:[1,0]
	v_pk_mul_f32 v[200:201], v[200:201], v[240:241] op_sel_hi:[1,0]
	v_pk_mul_f32 v[202:203], v[202:203], v[240:241] op_sel_hi:[1,0]
	v_pk_mul_f32 v[204:205], v[204:205], v[240:241] op_sel_hi:[1,0]
	v_pk_mul_f32 v[206:207], v[206:207], v[240:241] op_sel_hi:[1,0]
	v_pk_mul_f32 v[208:209], v[208:209], v[240:241] op_sel_hi:[1,0]
	v_pk_mul_f32 v[210:211], v[210:211], v[240:241] op_sel_hi:[1,0]
	v_pk_mul_f32 v[212:213], v[212:213], v[240:241] op_sel_hi:[1,0]
	v_pk_mul_f32 v[214:215], v[214:215], v[240:241] op_sel_hi:[1,0]
	v_mov_b32_e32 v240, 1.0
	v_mov_b32_e32 v88, 1.0
.Lgdn_nomat_2:
	v_mov_b32_e32 v238, v240
	s_nop 7
	v_pk_mul_f32 v[86:87], v[82:83], v[88:89] op_sel_hi:[1,0]
	s_nop 1
	v_mfma_f32_16x16x4_f32 v[184:187], v54, v86, v[184:187]
	v_mfma_f32_16x16x4_f32 v[188:191], v55, v86, v[188:191]
	v_mfma_f32_16x16x4_f32 v[192:195], v56, v86, v[192:195]
	v_mfma_f32_16x16x4_f32 v[196:199], v57, v86, v[196:199]
	v_mfma_f32_16x16x4_f32 v[200:203], v58, v86, v[200:203]
	v_mfma_f32_16x16x4_f32 v[204:207], v59, v86, v[204:207]
	v_mfma_f32_16x16x4_f32 v[208:211], v60, v86, v[208:211]
	v_mfma_f32_16x16x4_f32 v[212:215], v61, v86, v[212:215]
	v_mfma_f32_16x16x4_f32 v[184:187], v62, v87, v[184:187]
	v_mfma_f32_16x16x4_f32 v[188:191], v63, v87, v[188:191]
	v_mfma_f32_16x16x4_f32 v[192:195], v64, v87, v[192:195]
	v_mfma_f32_16x16x4_f32 v[196:199], v65, v87, v[196:199]
	v_mfma_f32_16x16x4_f32 v[200:203], v66, v87, v[200:203]
	v_mfma_f32_16x16x4_f32 v[204:207], v67, v87, v[204:207]
	v_mfma_f32_16x16x4_f32 v[208:211], v68, v87, v[208:211]
	v_mfma_f32_16x16x4_f32 v[212:215], v69, v87, v[212:215]
	ds_write2st64_b32 v172, v84, v85 offset0:16 offset1:20
	s_mov_b64 exec, s[40:41]
	ds_add_u32 v236, v237 offset:8
	s_mov_b64 exec, -1
	s_waitcnt lgkmcnt(2)
	v_mfma_f32_16x16x4_f32 v[96:99], v22, v184, 0
	v_mfma_f32_16x16x4_f32 v[100:103], v23, v185, 0
	v_mfma_f32_16x16x4_f32 v[96:99], v24, v186, v[96:99]
	v_mfma_f32_16x16x4_f32 v[100:103], v25, v187, v[100:103]
	ds_read_b32 v54, v170 offset:12672
	ds_read_b32 v55, v170 offset:12736
	ds_read_b32 v56, v170 offset:12800
	ds_read_b32 v57, v170 offset:12864
	v_mfma_f32_16x16x4_f32 v[96:99], v26, v188, v[96:99]
	v_mfma_f32_16x16x4_f32 v[100:103], v27, v189, v[100:103]
	v_mfma_f32_16x16x4_f32 v[96:99], v28, v190, v[96:99]
	v_mfma_f32_16x16x4_f32 v[100:103], v29, v191, v[100:103]
	ds_read_b128 v[22:25], v169 offset:16896
	ds_read_b32 v58, v170 offset:12928
	ds_read_b32 v59, v170 offset:12992
	ds_read_b32 v60, v170 offset:13056
	ds_read_b32 v61, v170 offset:13120
	v_mfma_f32_16x16x4_f32 v[96:99], v30, v192, v[96:99]
	v_mfma_f32_16x16x4_f32 v[100:103], v31, v193, v[100:103]
	v_mfma_f32_16x16x4_f32 v[96:99], v32, v194, v[96:99]
	v_mfma_f32_16x16x4_f32 v[100:103], v33, v195, v[100:103]
	ds_read_b128 v[26:29], v169 offset:16960
	ds_read_b32 v62, v170 offset:14784
	ds_read_b32 v63, v170 offset:14848
	ds_read_b32 v64, v170 offset:14912
	ds_read_b32 v65, v170 offset:14976
	v_mfma_f32_16x16x4_f32 v[96:99], v34, v196, v[96:99]
	v_mfma_f32_16x16x4_f32 v[100:103], v35, v197, v[100:103]
	v_mfma_f32_16x16x4_f32 v[96:99], v36, v198, v[96:99]
	v_mfma_f32_16x16x4_f32 v[100:103], v37, v199, v[100:103]
	ds_read_b128 v[30:33], v169 offset:17024
	ds_read_b32 v66, v170 offset:15040
	ds_read_b32 v67, v170 offset:15104
	ds_read_b32 v68, v170 offset:15168
	ds_read_b32 v69, v170 offset:15232
	v_mfma_f32_16x16x4_f32 v[96:99], v38, v200, v[96:99]
	v_mfma_f32_16x16x4_f32 v[100:103], v39, v201, v[100:103]
	v_mfma_f32_16x16x4_f32 v[96:99], v40, v202, v[96:99]
	v_mfma_f32_16x16x4_f32 v[100:103], v41, v203, v[100:103]
	ds_read_b128 v[34:37], v169 offset:17088
	ds_read_b32 v95, v175 offset:380
	ds_read2_b32 v[72:73], v174 offset0:24 offset1:28
	ds_read2_b32 v[74:75], v176 offset0:24 offset1:28
	ds_read2st64_b32 v[70:71], v171 offset0:24 offset1:28
	ds_read_b32 v93, v173 offset:1536
	ds_read_b32 v90, v173 offset:1552
	v_mfma_f32_16x16x4_f32 v[96:99], v42, v204, v[96:99]
	v_mfma_f32_16x16x4_f32 v[100:103], v43, v205, v[100:103]
	v_mfma_f32_16x16x4_f32 v[96:99], v44, v206, v[96:99]
	v_mfma_f32_16x16x4_f32 v[100:103], v45, v207, v[100:103]
	ds_read_b128 v[38:41], v169 offset:17152
	v_mfma_f32_16x16x4_f32 v[96:99], v46, v208, v[96:99]
	v_mfma_f32_16x16x4_f32 v[100:103], v47, v209, v[100:103]
	v_mfma_f32_16x16x4_f32 v[96:99], v48, v210, v[96:99]
	v_mfma_f32_16x16x4_f32 v[100:103], v49, v211, v[100:103]
	ds_read_b128 v[42:45], v169 offset:17216
	v_mfma_f32_16x16x4_f32 v[96:99], v50, v212, v[96:99]
	v_mfma_f32_16x16x4_f32 v[100:103], v51, v213, v[100:103]
	v_mfma_f32_16x16x4_f32 v[96:99], v52, v214, v[96:99]
	v_mfma_f32_16x16x4_f32 v[100:103], v53, v215, v[100:103]
	ds_read_b128 v[46:49], v169 offset:17280
	ds_read_b128 v[50:53], v169 offset:17344
	s_waitcnt lgkmcnt(4)
	v_mul_f32_e32 v240, v238, v95
	v_pk_mul_f32 v[76:77], v[72:73], v[238:239] op_sel_hi:[1,0]
	v_pk_mul_f32 v[78:79], v[74:75], v[238:239] op_sel_hi:[1,0]
	v_rcp_f32_e32 v88, v240
	v_readfirstlane_b32 s0, v240
	s_nop 3
	v_pk_add_f32 v[96:97], v[96:97], v[100:101]
	v_pk_add_f32 v[98:99], v[98:99], v[102:103]
	v_pk_fma_f32 v[80:81], v[76:77], v[96:97], v[70:71]
	v_pk_mul_f32 v[234:235], v[78:79], v[98:99]
	s_nop 1
	v_mfma_f32_16x16x4_f32 v[82:85], v93, v80, v[232:235]
	v_mfma_f32_16x16x4_f32 v[82:85], v90, v81, v[82:85]
	s_cmp_lt_u32 s0, 0x2b800000
	s_cbranch_scc0 .Lgdn_nomat_3
	v_pk_mul_f32 v[184:185], v[184:185], v[240:241] op_sel_hi:[1,0]
	v_pk_mul_f32 v[186:187], v[186:187], v[240:241] op_sel_hi:[1,0]
	v_pk_mul_f32 v[188:189], v[188:189], v[240:241] op_sel_hi:[1,0]
	v_pk_mul_f32 v[190:191], v[190:191], v[240:241] op_sel_hi:[1,0]
	v_pk_mul_f32 v[192:193], v[192:193], v[240:241] op_sel_hi:[1,0]
	v_pk_mul_f32 v[194:195], v[194:195], v[240:241] op_sel_hi:[1,0]
	v_pk_mul_f32 v[196:197], v[196:197], v[240:241] op_sel_hi:[1,0]
	v_pk_mul_f32 v[198:199], v[198:199], v[240:241] op_sel_hi:[1,0]
	v_pk_mul_f32 v[200:201], v[200:201], v[240:241] op_sel_hi:[1,0]
	v_pk_mul_f32 v[202:203], v[202:203], v[240:241] op_sel_hi:[1,0]
	v_pk_mul_f32 v[204:205], v[204:205], v[240:241] op_sel_hi:[1,0]
	v_pk_mul_f32 v[206:207], v[206:207], v[240:241] op_sel_hi:[1,0]
	v_pk_mul_f32 v[208:209], v[208:209], v[240:241] op_sel_hi:[1,0]
	v_pk_mul_f32 v[210:211], v[210:211], v[240:241] op_sel_hi:[1,0]
	v_pk_mul_f32 v[212:213], v[212:213], v[240:241] op_sel_hi:[1,0]
	v_pk_mul_f32 v[214:215], v[214:215], v[240:241] op_sel_hi:[1,0]
	v_mov_b32_e32 v240, 1.0
	v_mov_b32_e32 v88, 1.0
.Lgdn_nomat_3:
	v_mov_b32_e32 v238, v240
	s_nop 7
	v_pk_mul_f32 v[86:87], v[82:83], v[88:89] op_sel_hi:[1,0]
	s_nop 1
	v_mfma_f32_16x16x4_f32 v[184:187], v54, v86, v[184:187]
	v_mfma_f32_16x16x4_f32 v[188:191], v55, v86, v[188:191]
	v_mfma_f32_16x16x4_f32 v[192:195], v56, v86, v[192:195]
	v_mfma_f32_16x16x4_f32 v[196:199], v57, v86, v[196:199]
	v_mfma_f32_16x16x4_f32 v[200:203], v58, v86, v[200:203]
	v_mfma_f32_16x16x4_f32 v[204:207], v59, v86, v[204:207]
	v_mfma_f32_16x16x4_f32 v[208:211], v60, v86, v[208:211]
	v_mfma_f32_16x16x4_f32 v[212:215], v61, v86, v[212:215]
	v_mfma_f32_16x16x4_f32 v[184:187], v62, v87, v[184:187]
	v_mfma_f32_16x16x4_f32 v[188:191], v63, v87, v[188:191]
	v_mfma_f32_16x16x4_f32 v[192:195], v64, v87, v[192:195]
	v_mfma_f32_16x16x4_f32 v[196:199], v65, v87, v[196:199]
	v_mfma_f32_16x16x4_f32 v[200:203], v66, v87, v[200:203]
	v_mfma_f32_16x16x4_f32 v[204:207], v67, v87, v[204:207]
	v_mfma_f32_16x16x4_f32 v[208:211], v68, v87, v[208:211]
	v_mfma_f32_16x16x4_f32 v[212:215], v69, v87, v[212:215]
	ds_write2st64_b32 v172, v84, v85 offset0:24 offset1:28
	s_mov_b64 exec, s[40:41]
	ds_add_u32 v236, v237 offset:12
	s_mov_b64 exec, -1
	s_waitcnt lgkmcnt(2)
	v_mfma_f32_16x16x4_f32 v[96:99], v22, v184, 0
	v_mfma_f32_16x16x4_f32 v[100:103], v23, v185, 0
	v_mfma_f32_16x16x4_f32 v[96:99], v24, v186, v[96:99]
	v_mfma_f32_16x16x4_f32 v[100:103], v25, v187, v[100:103]
	ds_read_b32 v54, v170 offset:16896
	ds_read_b32 v55, v170 offset:16960
	ds_read_b32 v56, v170 offset:17024
	ds_read_b32 v57, v170 offset:17088
	v_mfma_f32_16x16x4_f32 v[96:99], v26, v188, v[96:99]
	v_mfma_f32_16x16x4_f32 v[100:103], v27, v189, v[100:103]
	v_mfma_f32_16x16x4_f32 v[96:99], v28, v190, v[96:99]
	v_mfma_f32_16x16x4_f32 v[100:103], v29, v191, v[100:103]
	ds_read_b128 v[22:25], v169 offset:21120
	ds_read_b32 v58, v170 offset:17152
	ds_read_b32 v59, v170 offset:17216
	ds_read_b32 v60, v170 offset:17280
	ds_read_b32 v61, v170 offset:17344
	v_mfma_f32_16x16x4_f32 v[96:99], v30, v192, v[96:99]
	v_mfma_f32_16x16x4_f32 v[100:103], v31, v193, v[100:103]
	v_mfma_f32_16x16x4_f32 v[96:99], v32, v194, v[96:99]
	v_mfma_f32_16x16x4_f32 v[100:103], v33, v195, v[100:103]
	ds_read_b128 v[26:29], v169 offset:21184
	ds_read_b32 v62, v170 offset:19008
	ds_read_b32 v63, v170 offset:19072
	ds_read_b32 v64, v170 offset:19136
	ds_read_b32 v65, v170 offset:19200
	v_mfma_f32_16x16x4_f32 v[96:99], v34, v196, v[96:99]
	v_mfma_f32_16x16x4_f32 v[100:103], v35, v197, v[100:103]
	v_mfma_f32_16x16x4_f32 v[96:99], v36, v198, v[96:99]
	v_mfma_f32_16x16x4_f32 v[100:103], v37, v199, v[100:103]
	ds_read_b128 v[30:33], v169 offset:21248
	ds_read_b32 v66, v170 offset:19264
	ds_read_b32 v67, v170 offset:19328
	ds_read_b32 v68, v170 offset:19392
	ds_read_b32 v69, v170 offset:19456
	v_mfma_f32_16x16x4_f32 v[96:99], v38, v200, v[96:99]
	v_mfma_f32_16x16x4_f32 v[100:103], v39, v201, v[100:103]
	v_mfma_f32_16x16x4_f32 v[96:99], v40, v202, v[96:99]
	v_mfma_f32_16x16x4_f32 v[100:103], v41, v203, v[100:103]
	ds_read_b128 v[34:37], v169 offset:21312
	ds_read_b32 v95, v175 offset:412
	ds_read2_b32 v[72:73], v174 offset0:32 offset1:36
	ds_read2_b32 v[74:75], v176 offset0:32 offset1:36
	ds_read2st64_b32 v[70:71], v171 offset0:32 offset1:36
	ds_read_b32 v93, v173 offset:2048
	ds_read_b32 v90, v173 offset:2064
	v_mfma_f32_16x16x4_f32 v[96:99], v42, v204, v[96:99]
	v_mfma_f32_16x16x4_f32 v[100:103], v43, v205, v[100:103]
	v_mfma_f32_16x16x4_f32 v[96:99], v44, v206, v[96:99]
	v_mfma_f32_16x16x4_f32 v[100:103], v45, v207, v[100:103]
	ds_read_b128 v[38:41], v169 offset:21376
	v_mfma_f32_16x16x4_f32 v[96:99], v46, v208, v[96:99]
	v_mfma_f32_16x16x4_f32 v[100:103], v47, v209, v[100:103]
	v_mfma_f32_16x16x4_f32 v[96:99], v48, v210, v[96:99]
	v_mfma_f32_16x16x4_f32 v[100:103], v49, v211, v[100:103]
	ds_read_b128 v[42:45], v169 offset:21440
	v_mfma_f32_16x16x4_f32 v[96:99], v50, v212, v[96:99]
	v_mfma_f32_16x16x4_f32 v[100:103], v51, v213, v[100:103]
	v_mfma_f32_16x16x4_f32 v[96:99], v52, v214, v[96:99]
	v_mfma_f32_16x16x4_f32 v[100:103], v53, v215, v[100:103]
	ds_read_b128 v[46:49], v169 offset:21504
	ds_read_b128 v[50:53], v169 offset:21568
	s_waitcnt lgkmcnt(4)
	v_mul_f32_e32 v240, v238, v95
	v_pk_mul_f32 v[76:77], v[72:73], v[238:239] op_sel_hi:[1,0]
	v_pk_mul_f32 v[78:79], v[74:75], v[238:239] op_sel_hi:[1,0]
	v_rcp_f32_e32 v88, v240
	v_readfirstlane_b32 s0, v240
	s_nop 3
	v_pk_add_f32 v[96:97], v[96:97], v[100:101]
	v_pk_add_f32 v[98:99], v[98:99], v[102:103]
	v_pk_fma_f32 v[80:81], v[76:77], v[96:97], v[70:71]
	v_pk_mul_f32 v[234:235], v[78:79], v[98:99]
	s_nop 1
	v_mfma_f32_16x16x4_f32 v[82:85], v93, v80, v[232:235]
	v_mfma_f32_16x16x4_f32 v[82:85], v90, v81, v[82:85]
	s_cmp_lt_u32 s0, 0x2b800000
	s_cbranch_scc0 .Lgdn_nomat_4
	v_pk_mul_f32 v[184:185], v[184:185], v[240:241] op_sel_hi:[1,0]
	v_pk_mul_f32 v[186:187], v[186:187], v[240:241] op_sel_hi:[1,0]
	v_pk_mul_f32 v[188:189], v[188:189], v[240:241] op_sel_hi:[1,0]
	v_pk_mul_f32 v[190:191], v[190:191], v[240:241] op_sel_hi:[1,0]
	v_pk_mul_f32 v[192:193], v[192:193], v[240:241] op_sel_hi:[1,0]
	v_pk_mul_f32 v[194:195], v[194:195], v[240:241] op_sel_hi:[1,0]
	v_pk_mul_f32 v[196:197], v[196:197], v[240:241] op_sel_hi:[1,0]
	v_pk_mul_f32 v[198:199], v[198:199], v[240:241] op_sel_hi:[1,0]
	v_pk_mul_f32 v[200:201], v[200:201], v[240:241] op_sel_hi:[1,0]
	v_pk_mul_f32 v[202:203], v[202:203], v[240:241] op_sel_hi:[1,0]
	v_pk_mul_f32 v[204:205], v[204:205], v[240:241] op_sel_hi:[1,0]
	v_pk_mul_f32 v[206:207], v[206:207], v[240:241] op_sel_hi:[1,0]
	v_pk_mul_f32 v[208:209], v[208:209], v[240:241] op_sel_hi:[1,0]
	v_pk_mul_f32 v[210:211], v[210:211], v[240:241] op_sel_hi:[1,0]
	v_pk_mul_f32 v[212:213], v[212:213], v[240:241] op_sel_hi:[1,0]
	v_pk_mul_f32 v[214:215], v[214:215], v[240:241] op_sel_hi:[1,0]
	v_mov_b32_e32 v240, 1.0
	v_mov_b32_e32 v88, 1.0
.Lgdn_nomat_4:
	v_mov_b32_e32 v238, v240
	s_nop 7
	v_pk_mul_f32 v[86:87], v[82:83], v[88:89] op_sel_hi:[1,0]
	s_nop 1
	v_mfma_f32_16x16x4_f32 v[184:187], v54, v86, v[184:187]
	v_mfma_f32_16x16x4_f32 v[188:191], v55, v86, v[188:191]
	v_mfma_f32_16x16x4_f32 v[192:195], v56, v86, v[192:195]
	v_mfma_f32_16x16x4_f32 v[196:199], v57, v86, v[196:199]
	v_mfma_f32_16x16x4_f32 v[200:203], v58, v86, v[200:203]
	v_mfma_f32_16x16x4_f32 v[204:207], v59, v86, v[204:207]
	v_mfma_f32_16x16x4_f32 v[208:211], v60, v86, v[208:211]
	v_mfma_f32_16x16x4_f32 v[212:215], v61, v86, v[212:215]
	v_mfma_f32_16x16x4_f32 v[184:187], v62, v87, v[184:187]
	v_mfma_f32_16x16x4_f32 v[188:191], v63, v87, v[188:191]
	v_mfma_f32_16x16x4_f32 v[192:195], v64, v87, v[192:195]
	v_mfma_f32_16x16x4_f32 v[196:199], v65, v87, v[196:199]
	v_mfma_f32_16x16x4_f32 v[200:203], v66, v87, v[200:203]
	v_mfma_f32_16x16x4_f32 v[204:207], v67, v87, v[204:207]
	v_mfma_f32_16x16x4_f32 v[208:211], v68, v87, v[208:211]
	v_mfma_f32_16x16x4_f32 v[212:215], v69, v87, v[212:215]
	ds_write2st64_b32 v172, v84, v85 offset0:32 offset1:36
	s_mov_b64 exec, s[40:41]
	ds_add_u32 v236, v237 offset:16
	s_mov_b64 exec, -1
	s_waitcnt lgkmcnt(2)
	v_mfma_f32_16x16x4_f32 v[96:99], v22, v184, 0
	v_mfma_f32_16x16x4_f32 v[100:103], v23, v185, 0
	v_mfma_f32_16x16x4_f32 v[96:99], v24, v186, v[96:99]
	v_mfma_f32_16x16x4_f32 v[100:103], v25, v187, v[100:103]
	ds_read_b32 v54, v170 offset:21120
	ds_read_b32 v55, v170 offset:21184
	ds_read_b32 v56, v170 offset:21248
	ds_read_b32 v57, v170 offset:21312
	v_mfma_f32_16x16x4_f32 v[96:99], v26, v188, v[96:99]
	v_mfma_f32_16x16x4_f32 v[100:103], v27, v189, v[100:103]
	v_mfma_f32_16x16x4_f32 v[96:99], v28, v190, v[96:99]
	v_mfma_f32_16x16x4_f32 v[100:103], v29, v191, v[100:103]
	ds_read_b128 v[22:25], v169 offset:25344
	ds_read_b32 v58, v170 offset:21376
	ds_read_b32 v59, v170 offset:21440
	ds_read_b32 v60, v170 offset:21504
	ds_read_b32 v61, v170 offset:21568
	v_mfma_f32_16x16x4_f32 v[96:99], v30, v192, v[96:99]
	v_mfma_f32_16x16x4_f32 v[100:103], v31, v193, v[100:103]
	v_mfma_f32_16x16x4_f32 v[96:99], v32, v194, v[96:99]
	v_mfma_f32_16x16x4_f32 v[100:103], v33, v195, v[100:103]
	ds_read_b128 v[26:29], v169 offset:25408
	ds_read_b32 v62, v170 offset:23232
	ds_read_b32 v63, v170 offset:23296
	ds_read_b32 v64, v170 offset:23360
	ds_read_b32 v65, v170 offset:23424
	v_mfma_f32_16x16x4_f32 v[96:99], v34, v196, v[96:99]
	v_mfma_f32_16x16x4_f32 v[100:103], v35, v197, v[100:103]
	v_mfma_f32_16x16x4_f32 v[96:99], v36, v198, v[96:99]
	v_mfma_f32_16x16x4_f32 v[100:103], v37, v199, v[100:103]
	ds_read_b128 v[30:33], v169 offset:25472
	ds_read_b32 v66, v170 offset:23488
	ds_read_b32 v67, v170 offset:23552
	ds_read_b32 v68, v170 offset:23616
	ds_read_b32 v69, v170 offset:23680
	v_mfma_f32_16x16x4_f32 v[96:99], v38, v200, v[96:99]
	v_mfma_f32_16x16x4_f32 v[100:103], v39, v201, v[100:103]
	v_mfma_f32_16x16x4_f32 v[96:99], v40, v202, v[96:99]
	v_mfma_f32_16x16x4_f32 v[100:103], v41, v203, v[100:103]
	ds_read_b128 v[34:37], v169 offset:25536
	ds_read_b32 v95, v175 offset:444
	ds_read2_b32 v[72:73], v174 offset0:40 offset1:44
	ds_read2_b32 v[74:75], v176 offset0:40 offset1:44
	ds_read2st64_b32 v[70:71], v171 offset0:40 offset1:44
	ds_read_b32 v93, v173 offset:2560
	ds_read_b32 v90, v173 offset:2576
	v_mfma_f32_16x16x4_f32 v[96:99], v42, v204, v[96:99]
	v_mfma_f32_16x16x4_f32 v[100:103], v43, v205, v[100:103]
	v_mfma_f32_16x16x4_f32 v[96:99], v44, v206, v[96:99]
	v_mfma_f32_16x16x4_f32 v[100:103], v45, v207, v[100:103]
	ds_read_b128 v[38:41], v169 offset:25600
	v_mfma_f32_16x16x4_f32 v[96:99], v46, v208, v[96:99]
	v_mfma_f32_16x16x4_f32 v[100:103], v47, v209, v[100:103]
	v_mfma_f32_16x16x4_f32 v[96:99], v48, v210, v[96:99]
	v_mfma_f32_16x16x4_f32 v[100:103], v49, v211, v[100:103]
	ds_read_b128 v[42:45], v169 offset:25664
	v_mfma_f32_16x16x4_f32 v[96:99], v50, v212, v[96:99]
	v_mfma_f32_16x16x4_f32 v[100:103], v51, v213, v[100:103]
	v_mfma_f32_16x16x4_f32 v[96:99], v52, v214, v[96:99]
	v_mfma_f32_16x16x4_f32 v[100:103], v53, v215, v[100:103]
	ds_read_b128 v[46:49], v169 offset:25728
	ds_read_b128 v[50:53], v169 offset:25792
	s_waitcnt lgkmcnt(4)
	v_mul_f32_e32 v240, v238, v95
	v_pk_mul_f32 v[76:77], v[72:73], v[238:239] op_sel_hi:[1,0]
	v_pk_mul_f32 v[78:79], v[74:75], v[238:239] op_sel_hi:[1,0]
	v_rcp_f32_e32 v88, v240
	v_readfirstlane_b32 s0, v240
	s_nop 3
	v_pk_add_f32 v[96:97], v[96:97], v[100:101]
	v_pk_add_f32 v[98:99], v[98:99], v[102:103]
	v_pk_fma_f32 v[80:81], v[76:77], v[96:97], v[70:71]
	v_pk_mul_f32 v[234:235], v[78:79], v[98:99]
	s_nop 1
	v_mfma_f32_16x16x4_f32 v[82:85], v93, v80, v[232:235]
	v_mfma_f32_16x16x4_f32 v[82:85], v90, v81, v[82:85]
	s_cmp_lt_u32 s0, 0x2b800000
	s_cbranch_scc0 .Lgdn_nomat_5
	v_pk_mul_f32 v[184:185], v[184:185], v[240:241] op_sel_hi:[1,0]
	v_pk_mul_f32 v[186:187], v[186:187], v[240:241] op_sel_hi:[1,0]
	v_pk_mul_f32 v[188:189], v[188:189], v[240:241] op_sel_hi:[1,0]
	v_pk_mul_f32 v[190:191], v[190:191], v[240:241] op_sel_hi:[1,0]
	v_pk_mul_f32 v[192:193], v[192:193], v[240:241] op_sel_hi:[1,0]
	v_pk_mul_f32 v[194:195], v[194:195], v[240:241] op_sel_hi:[1,0]
	v_pk_mul_f32 v[196:197], v[196:197], v[240:241] op_sel_hi:[1,0]
	v_pk_mul_f32 v[198:199], v[198:199], v[240:241] op_sel_hi:[1,0]
	v_pk_mul_f32 v[200:201], v[200:201], v[240:241] op_sel_hi:[1,0]
	v_pk_mul_f32 v[202:203], v[202:203], v[240:241] op_sel_hi:[1,0]
	v_pk_mul_f32 v[204:205], v[204:205], v[240:241] op_sel_hi:[1,0]
	v_pk_mul_f32 v[206:207], v[206:207], v[240:241] op_sel_hi:[1,0]
	v_pk_mul_f32 v[208:209], v[208:209], v[240:241] op_sel_hi:[1,0]
	v_pk_mul_f32 v[210:211], v[210:211], v[240:241] op_sel_hi:[1,0]
	v_pk_mul_f32 v[212:213], v[212:213], v[240:241] op_sel_hi:[1,0]
	v_pk_mul_f32 v[214:215], v[214:215], v[240:241] op_sel_hi:[1,0]
	v_mov_b32_e32 v240, 1.0
	v_mov_b32_e32 v88, 1.0
.Lgdn_nomat_5:
	v_mov_b32_e32 v238, v240
	s_nop 7
	v_pk_mul_f32 v[86:87], v[82:83], v[88:89] op_sel_hi:[1,0]
	s_nop 1
	v_mfma_f32_16x16x4_f32 v[184:187], v54, v86, v[184:187]
	v_mfma_f32_16x16x4_f32 v[188:191], v55, v86, v[188:191]
	v_mfma_f32_16x16x4_f32 v[192:195], v56, v86, v[192:195]
	v_mfma_f32_16x16x4_f32 v[196:199], v57, v86, v[196:199]
	v_mfma_f32_16x16x4_f32 v[200:203], v58, v86, v[200:203]
	v_mfma_f32_16x16x4_f32 v[204:207], v59, v86, v[204:207]
	v_mfma_f32_16x16x4_f32 v[208:211], v60, v86, v[208:211]
	v_mfma_f32_16x16x4_f32 v[212:215], v61, v86, v[212:215]
	v_mfma_f32_16x16x4_f32 v[184:187], v62, v87, v[184:187]
	v_mfma_f32_16x16x4_f32 v[188:191], v63, v87, v[188:191]
	v_mfma_f32_16x16x4_f32 v[192:195], v64, v87, v[192:195]
	v_mfma_f32_16x16x4_f32 v[196:199], v65, v87, v[196:199]
	v_mfma_f32_16x16x4_f32 v[200:203], v66, v87, v[200:203]
	v_mfma_f32_16x16x4_f32 v[204:207], v67, v87, v[204:207]
	v_mfma_f32_16x16x4_f32 v[208:211], v68, v87, v[208:211]
	v_mfma_f32_16x16x4_f32 v[212:215], v69, v87, v[212:215]
	ds_write2st64_b32 v172, v84, v85 offset0:40 offset1:44
	s_mov_b64 exec, s[40:41]
	ds_add_u32 v236, v237 offset:20
	s_mov_b64 exec, -1
	s_waitcnt lgkmcnt(2)
	v_mfma_f32_16x16x4_f32 v[96:99], v22, v184, 0
	v_mfma_f32_16x16x4_f32 v[100:103], v23, v185, 0
	v_mfma_f32_16x16x4_f32 v[96:99], v24, v186, v[96:99]
	v_mfma_f32_16x16x4_f32 v[100:103], v25, v187, v[100:103]
	ds_read_b32 v54, v170 offset:25344
	ds_read_b32 v55, v170 offset:25408
	ds_read_b32 v56, v170 offset:25472
	ds_read_b32 v57, v170 offset:25536
	v_mfma_f32_16x16x4_f32 v[96:99], v26, v188, v[96:99]
	v_mfma_f32_16x16x4_f32 v[100:103], v27, v189, v[100:103]
	v_mfma_f32_16x16x4_f32 v[96:99], v28, v190, v[96:99]
	v_mfma_f32_16x16x4_f32 v[100:103], v29, v191, v[100:103]
	ds_read_b128 v[22:25], v169 offset:29568
	ds_read_b32 v58, v170 offset:25600
	ds_read_b32 v59, v170 offset:25664
	ds_read_b32 v60, v170 offset:25728
	ds_read_b32 v61, v170 offset:25792
	v_mfma_f32_16x16x4_f32 v[96:99], v30, v192, v[96:99]
	v_mfma_f32_16x16x4_f32 v[100:103], v31, v193, v[100:103]
	v_mfma_f32_16x16x4_f32 v[96:99], v32, v194, v[96:99]
	v_mfma_f32_16x16x4_f32 v[100:103], v33, v195, v[100:103]
	ds_read_b128 v[26:29], v169 offset:29632
	ds_read_b32 v62, v170 offset:27456
	ds_read_b32 v63, v170 offset:27520
	ds_read_b32 v64, v170 offset:27584
	ds_read_b32 v65, v170 offset:27648
	v_mfma_f32_16x16x4_f32 v[96:99], v34, v196, v[96:99]
	v_mfma_f32_16x16x4_f32 v[100:103], v35, v197, v[100:103]
	v_mfma_f32_16x16x4_f32 v[96:99], v36, v198, v[96:99]
	v_mfma_f32_16x16x4_f32 v[100:103], v37, v199, v[100:103]
	ds_read_b128 v[30:33], v169 offset:29696
	ds_read_b32 v66, v170 offset:27712
	ds_read_b32 v67, v170 offset:27776
	ds_read_b32 v68, v170 offset:27840
	ds_read_b32 v69, v170 offset:27904
	v_mfma_f32_16x16x4_f32 v[96:99], v38, v200, v[96:99]
	v_mfma_f32_16x16x4_f32 v[100:103], v39, v201, v[100:103]
	v_mfma_f32_16x16x4_f32 v[96:99], v40, v202, v[96:99]
	v_mfma_f32_16x16x4_f32 v[100:103], v41, v203, v[100:103]
	ds_read_b128 v[34:37], v169 offset:29760
	ds_read_b32 v95, v175 offset:476
	ds_read2_b32 v[72:73], v174 offset0:48 offset1:52
	ds_read2_b32 v[74:75], v176 offset0:48 offset1:52
	ds_read2st64_b32 v[70:71], v171 offset0:48 offset1:52
	ds_read_b32 v93, v173 offset:3072
	ds_read_b32 v90, v173 offset:3088
	v_mfma_f32_16x16x4_f32 v[96:99], v42, v204, v[96:99]
	v_mfma_f32_16x16x4_f32 v[100:103], v43, v205, v[100:103]
	v_mfma_f32_16x16x4_f32 v[96:99], v44, v206, v[96:99]
	v_mfma_f32_16x16x4_f32 v[100:103], v45, v207, v[100:103]
	ds_read_b128 v[38:41], v169 offset:29824
	v_mfma_f32_16x16x4_f32 v[96:99], v46, v208, v[96:99]
	v_mfma_f32_16x16x4_f32 v[100:103], v47, v209, v[100:103]
	v_mfma_f32_16x16x4_f32 v[96:99], v48, v210, v[96:99]
	v_mfma_f32_16x16x4_f32 v[100:103], v49, v211, v[100:103]
	ds_read_b128 v[42:45], v169 offset:29888
	v_mfma_f32_16x16x4_f32 v[96:99], v50, v212, v[96:99]
	v_mfma_f32_16x16x4_f32 v[100:103], v51, v213, v[100:103]
	v_mfma_f32_16x16x4_f32 v[96:99], v52, v214, v[96:99]
	v_mfma_f32_16x16x4_f32 v[100:103], v53, v215, v[100:103]
	ds_read_b128 v[46:49], v169 offset:29952
	ds_read_b128 v[50:53], v169 offset:30016
	s_waitcnt lgkmcnt(4)
	v_mul_f32_e32 v240, v238, v95
	v_pk_mul_f32 v[76:77], v[72:73], v[238:239] op_sel_hi:[1,0]
	v_pk_mul_f32 v[78:79], v[74:75], v[238:239] op_sel_hi:[1,0]
	v_rcp_f32_e32 v88, v240
	v_readfirstlane_b32 s0, v240
	s_nop 3
	v_pk_add_f32 v[96:97], v[96:97], v[100:101]
	v_pk_add_f32 v[98:99], v[98:99], v[102:103]
	v_pk_fma_f32 v[80:81], v[76:77], v[96:97], v[70:71]
	v_pk_mul_f32 v[234:235], v[78:79], v[98:99]
	s_nop 1
	v_mfma_f32_16x16x4_f32 v[82:85], v93, v80, v[232:235]
	v_mfma_f32_16x16x4_f32 v[82:85], v90, v81, v[82:85]
	s_cmp_lt_u32 s0, 0x2b800000
	s_cbranch_scc0 .Lgdn_nomat_6
	v_pk_mul_f32 v[184:185], v[184:185], v[240:241] op_sel_hi:[1,0]
	v_pk_mul_f32 v[186:187], v[186:187], v[240:241] op_sel_hi:[1,0]
	v_pk_mul_f32 v[188:189], v[188:189], v[240:241] op_sel_hi:[1,0]
	v_pk_mul_f32 v[190:191], v[190:191], v[240:241] op_sel_hi:[1,0]
	v_pk_mul_f32 v[192:193], v[192:193], v[240:241] op_sel_hi:[1,0]
	v_pk_mul_f32 v[194:195], v[194:195], v[240:241] op_sel_hi:[1,0]
	v_pk_mul_f32 v[196:197], v[196:197], v[240:241] op_sel_hi:[1,0]
	v_pk_mul_f32 v[198:199], v[198:199], v[240:241] op_sel_hi:[1,0]
	v_pk_mul_f32 v[200:201], v[200:201], v[240:241] op_sel_hi:[1,0]
	v_pk_mul_f32 v[202:203], v[202:203], v[240:241] op_sel_hi:[1,0]
	v_pk_mul_f32 v[204:205], v[204:205], v[240:241] op_sel_hi:[1,0]
	v_pk_mul_f32 v[206:207], v[206:207], v[240:241] op_sel_hi:[1,0]
	v_pk_mul_f32 v[208:209], v[208:209], v[240:241] op_sel_hi:[1,0]
	v_pk_mul_f32 v[210:211], v[210:211], v[240:241] op_sel_hi:[1,0]
	v_pk_mul_f32 v[212:213], v[212:213], v[240:241] op_sel_hi:[1,0]
	v_pk_mul_f32 v[214:215], v[214:215], v[240:241] op_sel_hi:[1,0]
	v_mov_b32_e32 v240, 1.0
	v_mov_b32_e32 v88, 1.0
.Lgdn_nomat_6:
	v_mov_b32_e32 v238, v240
	s_nop 7
	v_pk_mul_f32 v[86:87], v[82:83], v[88:89] op_sel_hi:[1,0]
	s_nop 1
	v_mfma_f32_16x16x4_f32 v[184:187], v54, v86, v[184:187]
	v_mfma_f32_16x16x4_f32 v[188:191], v55, v86, v[188:191]
	v_mfma_f32_16x16x4_f32 v[192:195], v56, v86, v[192:195]
	v_mfma_f32_16x16x4_f32 v[196:199], v57, v86, v[196:199]
	v_mfma_f32_16x16x4_f32 v[200:203], v58, v86, v[200:203]
	v_mfma_f32_16x16x4_f32 v[204:207], v59, v86, v[204:207]
	v_mfma_f32_16x16x4_f32 v[208:211], v60, v86, v[208:211]
	v_mfma_f32_16x16x4_f32 v[212:215], v61, v86, v[212:215]
	v_mfma_f32_16x16x4_f32 v[184:187], v62, v87, v[184:187]
	v_mfma_f32_16x16x4_f32 v[188:191], v63, v87, v[188:191]
	v_mfma_f32_16x16x4_f32 v[192:195], v64, v87, v[192:195]
	v_mfma_f32_16x16x4_f32 v[196:199], v65, v87, v[196:199]
	v_mfma_f32_16x16x4_f32 v[200:203], v66, v87, v[200:203]
	v_mfma_f32_16x16x4_f32 v[204:207], v67, v87, v[204:207]
	v_mfma_f32_16x16x4_f32 v[208:211], v68, v87, v[208:211]
	v_mfma_f32_16x16x4_f32 v[212:215], v69, v87, v[212:215]
	ds_write2st64_b32 v172, v84, v85 offset0:48 offset1:52
	s_mov_b64 exec, s[40:41]
	ds_add_u32 v236, v237 offset:24
	s_mov_b64 exec, -1
	s_waitcnt lgkmcnt(2)
	v_mfma_f32_16x16x4_f32 v[96:99], v22, v184, 0
	v_mfma_f32_16x16x4_f32 v[100:103], v23, v185, 0
	v_mfma_f32_16x16x4_f32 v[96:99], v24, v186, v[96:99]
	v_mfma_f32_16x16x4_f32 v[100:103], v25, v187, v[100:103]
	ds_read_b32 v54, v170 offset:29568
	ds_read_b32 v55, v170 offset:29632
	ds_read_b32 v56, v170 offset:29696
	ds_read_b32 v57, v170 offset:29760
	v_mfma_f32_16x16x4_f32 v[96:99], v26, v188, v[96:99]
	v_mfma_f32_16x16x4_f32 v[100:103], v27, v189, v[100:103]
	v_mfma_f32_16x16x4_f32 v[96:99], v28, v190, v[96:99]
	v_mfma_f32_16x16x4_f32 v[100:103], v29, v191, v[100:103]
	ds_read_b128 v[22:25], v169 offset:33792
	ds_read_b32 v58, v170 offset:29824
	ds_read_b32 v59, v170 offset:29888
	ds_read_b32 v60, v170 offset:29952
	ds_read_b32 v61, v170 offset:30016
	v_mfma_f32_16x16x4_f32 v[96:99], v30, v192, v[96:99]
	v_mfma_f32_16x16x4_f32 v[100:103], v31, v193, v[100:103]
	v_mfma_f32_16x16x4_f32 v[96:99], v32, v194, v[96:99]
	v_mfma_f32_16x16x4_f32 v[100:103], v33, v195, v[100:103]
	ds_read_b128 v[26:29], v169 offset:33856
	ds_read_b32 v62, v170 offset:31680
	ds_read_b32 v63, v170 offset:31744
	ds_read_b32 v64, v170 offset:31808
	ds_read_b32 v65, v170 offset:31872
	v_mfma_f32_16x16x4_f32 v[96:99], v34, v196, v[96:99]
	v_mfma_f32_16x16x4_f32 v[100:103], v35, v197, v[100:103]
	v_mfma_f32_16x16x4_f32 v[96:99], v36, v198, v[96:99]
	v_mfma_f32_16x16x4_f32 v[100:103], v37, v199, v[100:103]
	ds_read_b128 v[30:33], v169 offset:33920
	ds_read_b32 v66, v170 offset:31936
	ds_read_b32 v67, v170 offset:32000
	ds_read_b32 v68, v170 offset:32064
	ds_read_b32 v69, v170 offset:32128
	v_mfma_f32_16x16x4_f32 v[96:99], v38, v200, v[96:99]
	v_mfma_f32_16x16x4_f32 v[100:103], v39, v201, v[100:103]
	v_mfma_f32_16x16x4_f32 v[96:99], v40, v202, v[96:99]
	v_mfma_f32_16x16x4_f32 v[100:103], v41, v203, v[100:103]
	ds_read_b128 v[34:37], v169 offset:33984
	ds_read_b32 v95, v175 offset:508
	ds_read2_b32 v[72:73], v174 offset0:56 offset1:60
	ds_read2_b32 v[74:75], v176 offset0:56 offset1:60
	ds_read2st64_b32 v[70:71], v171 offset0:56 offset1:60
	ds_read_b32 v93, v173 offset:3584
	ds_read_b32 v90, v173 offset:3600
	v_mfma_f32_16x16x4_f32 v[96:99], v42, v204, v[96:99]
	v_mfma_f32_16x16x4_f32 v[100:103], v43, v205, v[100:103]
	v_mfma_f32_16x16x4_f32 v[96:99], v44, v206, v[96:99]
	v_mfma_f32_16x16x4_f32 v[100:103], v45, v207, v[100:103]
	ds_read_b128 v[38:41], v169 offset:34048
	v_mfma_f32_16x16x4_f32 v[96:99], v46, v208, v[96:99]
	v_mfma_f32_16x16x4_f32 v[100:103], v47, v209, v[100:103]
	v_mfma_f32_16x16x4_f32 v[96:99], v48, v210, v[96:99]
	v_mfma_f32_16x16x4_f32 v[100:103], v49, v211, v[100:103]
	ds_read_b128 v[42:45], v169 offset:34112
	v_mfma_f32_16x16x4_f32 v[96:99], v50, v212, v[96:99]
	v_mfma_f32_16x16x4_f32 v[100:103], v51, v213, v[100:103]
	v_mfma_f32_16x16x4_f32 v[96:99], v52, v214, v[96:99]
	v_mfma_f32_16x16x4_f32 v[100:103], v53, v215, v[100:103]
	ds_read_b128 v[46:49], v169 offset:34176
	ds_read_b128 v[50:53], v169 offset:34240
	s_waitcnt lgkmcnt(4)
	v_mul_f32_e32 v240, v238, v95
	v_pk_mul_f32 v[76:77], v[72:73], v[238:239] op_sel_hi:[1,0]
	v_pk_mul_f32 v[78:79], v[74:75], v[238:239] op_sel_hi:[1,0]
	v_rcp_f32_e32 v88, v240
	v_readfirstlane_b32 s0, v240
	s_nop 3
	v_pk_add_f32 v[96:97], v[96:97], v[100:101]
	v_pk_add_f32 v[98:99], v[98:99], v[102:103]
	v_pk_fma_f32 v[80:81], v[76:77], v[96:97], v[70:71]
	v_pk_mul_f32 v[234:235], v[78:79], v[98:99]
	s_nop 1
	v_mfma_f32_16x16x4_f32 v[82:85], v93, v80, v[232:235]
	v_mfma_f32_16x16x4_f32 v[82:85], v90, v81, v[82:85]
	s_cmp_lt_u32 s0, 0x2b800000
	s_cbranch_scc0 .Lgdn_nomat_7
	v_pk_mul_f32 v[184:185], v[184:185], v[240:241] op_sel_hi:[1,0]
	v_pk_mul_f32 v[186:187], v[186:187], v[240:241] op_sel_hi:[1,0]
	v_pk_mul_f32 v[188:189], v[188:189], v[240:241] op_sel_hi:[1,0]
	v_pk_mul_f32 v[190:191], v[190:191], v[240:241] op_sel_hi:[1,0]
	v_pk_mul_f32 v[192:193], v[192:193], v[240:241] op_sel_hi:[1,0]
	v_pk_mul_f32 v[194:195], v[194:195], v[240:241] op_sel_hi:[1,0]
	v_pk_mul_f32 v[196:197], v[196:197], v[240:241] op_sel_hi:[1,0]
	v_pk_mul_f32 v[198:199], v[198:199], v[240:241] op_sel_hi:[1,0]
	v_pk_mul_f32 v[200:201], v[200:201], v[240:241] op_sel_hi:[1,0]
	v_pk_mul_f32 v[202:203], v[202:203], v[240:241] op_sel_hi:[1,0]
	v_pk_mul_f32 v[204:205], v[204:205], v[240:241] op_sel_hi:[1,0]
	v_pk_mul_f32 v[206:207], v[206:207], v[240:241] op_sel_hi:[1,0]
	v_pk_mul_f32 v[208:209], v[208:209], v[240:241] op_sel_hi:[1,0]
	v_pk_mul_f32 v[210:211], v[210:211], v[240:241] op_sel_hi:[1,0]
	v_pk_mul_f32 v[212:213], v[212:213], v[240:241] op_sel_hi:[1,0]
	v_pk_mul_f32 v[214:215], v[214:215], v[240:241] op_sel_hi:[1,0]
	v_mov_b32_e32 v240, 1.0
	v_mov_b32_e32 v88, 1.0
.Lgdn_nomat_7:
	v_mov_b32_e32 v238, v240
	s_nop 7
	v_pk_mul_f32 v[86:87], v[82:83], v[88:89] op_sel_hi:[1,0]
	s_nop 1
	v_mfma_f32_16x16x4_f32 v[184:187], v54, v86, v[184:187]
	v_mfma_f32_16x16x4_f32 v[188:191], v55, v86, v[188:191]
	v_mfma_f32_16x16x4_f32 v[192:195], v56, v86, v[192:195]
	v_mfma_f32_16x16x4_f32 v[196:199], v57, v86, v[196:199]
	v_mfma_f32_16x16x4_f32 v[200:203], v58, v86, v[200:203]
	v_mfma_f32_16x16x4_f32 v[204:207], v59, v86, v[204:207]
	v_mfma_f32_16x16x4_f32 v[208:211], v60, v86, v[208:211]
	v_mfma_f32_16x16x4_f32 v[212:215], v61, v86, v[212:215]
	v_mfma_f32_16x16x4_f32 v[184:187], v62, v87, v[184:187]
	v_mfma_f32_16x16x4_f32 v[188:191], v63, v87, v[188:191]
	v_mfma_f32_16x16x4_f32 v[192:195], v64, v87, v[192:195]
	v_mfma_f32_16x16x4_f32 v[196:199], v65, v87, v[196:199]
	v_mfma_f32_16x16x4_f32 v[200:203], v66, v87, v[200:203]
	v_mfma_f32_16x16x4_f32 v[204:207], v67, v87, v[204:207]
	v_mfma_f32_16x16x4_f32 v[208:211], v68, v87, v[208:211]
	v_mfma_f32_16x16x4_f32 v[212:215], v69, v87, v[212:215]
	ds_write2st64_b32 v172, v84, v85 offset0:56 offset1:60
	s_mov_b64 exec, s[40:41]
	ds_add_u32 v236, v237 offset:28
	s_mov_b64 exec, -1
	s_branch .Lgdn_done

.LBB0_563:
	s_or_b64 exec, exec, s[0:1]
	v_lshlrev_b64 v[2:3], 9, v[2:3]
	v_mov_b32_e32 v7, v94
	v_or_b32_e32 v2, v2, v1
	v_lshl_add_u64 v[4:5], v[4:5], 0, v[6:7]
	v_lshl_add_u64 v[8:9], v[2:3], 2, s[34:35]
	v_lshl_add_u64 v[6:7], v[2:3], 1, s[62:63]
	s_waitcnt vmcnt(4)
	v_lshl_add_u64 v[10:11], v[4:5], 0, s[76:77]
	global_load_dword v107, v[8:9], off
	global_load_ushort v18, v[4:5], off
	global_load_ushort v1, v[4:5], off offset:3072
	global_load_ushort v19, v[10:11], off offset:1024
	global_load_ushort v20, v[4:5], off offset:1024
	global_load_ushort v21, v[10:11], off offset:2048
	global_load_ushort v22, v[6:7], off
	global_load_ushort v23, v[4:5], off offset:2048
	v_or_b32_e32 v4, 0x200, v2
	v_mov_b32_e32 v5, v3
	v_lshl_add_u64 v[6:7], v[4:5], 1, s[62:63]
	v_lshl_add_u64 v[4:5], v[4:5], 2, s[34:35]
	v_or_b32_e32 v12, 0x400, v2
	v_mov_b32_e32 v13, v3
	v_lshl_add_u64 v[8:9], v[10:11], 0, s[76:77]
	s_waitcnt vmcnt(11)
	v_lshl_add_u64 v[14:15], v[12:13], 1, s[62:63]
	v_lshl_add_u64 v[12:13], v[12:13], 2, s[34:35]
	global_load_ushort v24, v[6:7], off
	global_load_dword v108, v[4:5], off
	global_load_ushort v25, v[8:9], off offset:3072
	global_load_ushort v26, v[8:9], off offset:1024
	global_load_ushort v27, v[14:15], off
	global_load_dword v109, v[12:13], off
	global_load_ushort v28, v[8:9], off offset:2048
	global_load_ushort v29, v[10:11], off offset:3072
	v_or_b32_e32 v4, 0x600, v2
	v_mov_b32_e32 v5, v3
	v_lshl_add_u64 v[16:17], v[8:9], 0, s[76:77]
	v_lshl_add_u64 v[6:7], v[4:5], 1, s[62:63]
	v_lshl_add_u64 v[4:5], v[4:5], 2, s[34:35]
	v_lshl_add_u64 v[8:9], v[16:17], 0, s[76:77]
	global_load_ushort v30, v[16:17], off offset:1024
	global_load_ushort v31, v[16:17], off offset:2048
	global_load_ushort v32, v[6:7], off
	global_load_dword v110, v[4:5], off
	global_load_ushort v33, v[8:9], off offset:3072
	global_load_ushort v36, v[8:9], off offset:1024
	global_load_ushort v37, v[8:9], off offset:2048
	s_nop 0
	global_load_ushort v16, v[16:17], off offset:3072
	v_or_b32_e32 v4, 0xa00, v2
	v_mov_b32_e32 v5, v3
	v_or_b32_e32 v10, 0x800, v2
	v_mov_b32_e32 v11, v3
	v_lshl_add_u64 v[14:15], v[8:9], 0, s[76:77]
	v_lshl_add_u64 v[6:7], v[4:5], 1, s[62:63]
	v_lshl_add_u64 v[4:5], v[4:5], 2, s[34:35]
	v_lshl_add_u64 v[12:13], v[10:11], 1, s[62:63]
	global_load_ushort v17, v[14:15], off offset:1024
	global_load_ushort v38, v[14:15], off offset:2048
	global_load_ushort v39, v[6:7], off
	global_load_dword v112, v[4:5], off
	global_load_ushort v40, v[14:15], off offset:3072
	global_load_ushort v41, v[12:13], off
	v_lshl_add_u64 v[4:5], v[14:15], 0, s[76:77]
	v_or_b32_e32 v6, 0xc00, v2
	v_mov_b32_e32 v7, v3
	v_lshl_add_u64 v[12:13], v[4:5], 0, s[76:77]
	v_or_b32_e32 v2, 0xe00, v2
	v_lshl_add_u64 v[8:9], v[6:7], 1, s[62:63]
	global_load_ushort v14, v[12:13], off offset:1024
	s_nop 0
	global_load_ushort v12, v[12:13], off offset:2048
	s_nop 0
	global_load_ushort v13, v[4:5], off offset:3072
	global_load_ushort v15, v[4:5], off offset:1024
	global_load_ushort v42, v[4:5], off offset:2048
	v_lshl_add_u64 v[4:5], v[2:3], 1, s[62:63]
	global_load_ushort v43, v[4:5], off
	s_nop 0
	global_load_ushort v8, v[8:9], off
	v_lshl_add_u64 v[4:5], v[6:7], 2, s[34:35]
	v_lshl_add_u64 v[2:3], v[2:3], 2, s[34:35]
	v_lshl_add_u64 v[10:11], v[10:11], 2, s[34:35]
	global_load_dword v113, v[4:5], off
	global_load_dword v114, v[2:3], off
	global_load_dword v111, v[10:11], off
	s_waitcnt vmcnt(38)
	v_lshlrev_b32_e32 v44, 16, v18
	s_waitcnt vmcnt(37)
	v_lshlrev_b32_e32 v1, 16, v1
	s_waitcnt vmcnt(36)
	v_lshlrev_b32_e32 v45, 16, v19
	s_waitcnt vmcnt(35)
	v_lshlrev_b32_e32 v46, 16, v20
	s_waitcnt vmcnt(34)
	v_lshlrev_b32_e32 v47, 16, v21
	s_waitcnt vmcnt(33)
	v_lshlrev_b32_e32 v50, 16, v22
	s_waitcnt vmcnt(32)
	v_lshlrev_b32_e32 v48, 16, v23
	s_waitcnt vmcnt(31)
	v_lshlrev_b32_e32 v51, 16, v24
	s_waitcnt vmcnt(29)
	v_lshlrev_b32_e32 v49, 16, v25
	s_waitcnt vmcnt(28)
	v_lshlrev_b32_e32 v54, 16, v26
	s_waitcnt vmcnt(27)
	v_lshlrev_b32_e32 v58, 16, v27
	s_waitcnt vmcnt(25)
	v_lshlrev_b32_e32 v56, 16, v28
	s_waitcnt vmcnt(24)
	v_lshlrev_b32_e32 v52, 16, v29
	s_waitcnt vmcnt(23)
	v_lshlrev_b32_e32 v53, 16, v30
	s_waitcnt vmcnt(22)
	v_lshlrev_b32_e32 v55, 16, v31
	s_waitcnt vmcnt(21)
	v_lshlrev_b32_e32 v57, 16, v32
	s_waitcnt vmcnt(19)
	v_lshlrev_b32_e32 v59, 16, v33
	s_waitcnt vmcnt(18)
	v_lshlrev_b32_e32 v62, 16, v36
	s_waitcnt vmcnt(17)
	v_lshlrev_b32_e32 v64, 16, v37
	s_waitcnt vmcnt(16)
	v_lshlrev_b32_e32 v60, 16, v16
	v_mov_b64_e32 v[36:37], v[94:95]
	s_waitcnt vmcnt(15)
	v_lshlrev_b32_e32 v61, 16, v17
	s_waitcnt vmcnt(14)
	v_lshlrev_b32_e32 v63, 16, v38
	s_waitcnt vmcnt(13)
	v_lshlrev_b32_e32 v65, 16, v39
	v_mov_b64_e32 v[38:39], v[94:95]
	s_waitcnt vmcnt(11)
	v_lshlrev_b32_e32 v67, 16, v40
	s_waitcnt vmcnt(10)
	v_lshlrev_b32_e32 v66, 16, v41
	v_mov_b64_e32 v[40:41], v[94:95]
	s_waitcnt vmcnt(9)
	v_lshlrev_b32_e32 v70, 16, v14
	s_waitcnt vmcnt(8)
	v_lshlrev_b32_e32 v72, 16, v12
	s_waitcnt vmcnt(7)
	v_lshlrev_b32_e32 v68, 16, v13
	s_waitcnt vmcnt(6)
	v_lshlrev_b32_e32 v69, 16, v15
	s_waitcnt vmcnt(5)
	v_lshlrev_b32_e32 v71, 16, v42
	s_waitcnt vmcnt(4)
	v_lshlrev_b32_e32 v73, 16, v43
	s_waitcnt vmcnt(3)
	v_lshlrev_b32_e32 v74, 16, v8
	v_mov_b64_e32 v[42:43], v[94:95]
	v_mov_b32_e32 v224, 0
	v_mov_b32_e32 v225, 0
	v_mov_b32_e32 v226, 0
	v_mov_b32_e32 v227, 0
	v_mov_b32_e32 v228, 0
	v_mov_b32_e32 v229, 0
	v_mov_b32_e32 v230, 0
	v_mov_b32_e32 v231, 0
	v_mov_b32_e32 v232, 0
	v_mov_b32_e32 v233, 0
	v_mov_b32_e32 v234, 0
	v_mov_b32_e32 v235, 0
	v_mov_b32_e32 v236, 0
	v_mov_b32_e32 v237, 0
	v_mov_b32_e32 v238, 0
	v_mov_b32_e32 v239, 0
	v_mov_b32_e32 v179, 0x27f00
	ds_write_b32 v179, v224 offset:0
	ds_write_b32 v179, v224 offset:4
	ds_write_b32 v179, v224 offset:8
	ds_write_b32 v179, v224 offset:12
	ds_write_b32 v179, v224 offset:16
	ds_write_b32 v179, v224 offset:20
	ds_write_b32 v179, v224 offset:24
	ds_write_b32 v179, v224 offset:28
	v_and_b32_e32 v124, 15, v77
	v_lshrrev_b32_e32 v125, 4, v77
	v_and_b32_e32 v102, 7, v124
	v_lshl_add_u32 v126, v75, 3, v102
	v_mul_u32_u24_e32 v126, 0x110, v126
	v_lshl_add_u32 v126, v125, 4, v126
	v_and_b32_e32 v127, 8, v124
	v_mul_u32_u24_e32 v127, 0x880, v127
	v_add_u32_e32 v79, v126, v127
	v_lshrrev_b32_e32 v126, 1, v125
	v_lshrrev_b32_e32 v127, 3, v124
	v_lshl_add_u32 v127, v126, 1, v127
	v_lshlrev_b32_e32 v86, 8, v127
	v_lshl_add_u32 v86, v75, 10, v86
	v_and_b32_e32 v127, 1, v125
	v_lshl_add_u32 v86, v127, 7, v86
	v_lshl_add_u32 v86, v102, 2, v86
	v_add_u32_e32 v86, 0x15800, v86
	v_sub_u32_e32 v87, 1, v126
	v_add_u32_e32 v87, v87, v102
	v_lshlrev_b32_e32 v127, 2, v127
	v_sub_u32_e32 v87, v87, v127
	v_max_i32_e32 v87, 0, v87
	v_lshlrev_b32_e32 v92, 10, v75
	v_add_u32_e32 v92, 0x15800, v92
	v_lshl_add_u32 v93, v125, 6, v92
	v_lshl_add_u32 v100, v102, 2, v92
	v_lshl_add_u32 v101, v102, 2, v93
	v_mov_b32_e32 v103, 1.0
	s_waitcnt vmcnt(0)
.LBB0_564:
	v_mov_b32_e32 v78, v75
	v_mov_b32_e32 v76, v77
	s_and_b32 s3, s40, 1
	v_add_u32_e32 v28, s72, v76
	v_ashrrev_i32_e32 v29, 31, v28
	v_lshlrev_b64 v[10:11], 2, v[28:29]
	s_and_b32 s3, s40, 1
	s_mov_b32 s0, 0x17800
	s_mov_b32 s1, 0x1b800
	s_cmp_eq_u32 s3, 0
	s_cselect_b32 s41, 0x11800, s0
	s_cselect_b32 s16, 0x23800, s1
	v_lshlrev_b32_e32 v26, 3, v78
	v_mul_u32_u24_e32 v166, 0x880, v78
	v_lshl_add_u32 v166, v76, 2, v166
	v_lshlrev_b32_e32 v167, 11, v78
	v_lshl_add_u32 v167, v76, 2, v167
	v_add_u32_e32 v167, s41, v167
	v_mov_b32_e32 v140, 1.0
	v_sub_f32_e32 v169, v106, v44
	v_sub_f32_e32 v170, v35, v46
	v_sub_f32_e32 v171, v34, v48
	v_fma_f32 v169, v169, v115, v44
	v_fma_f32 v170, v170, v116, v46
	v_fma_f32 v171, v171, v119, v48
	v_add_f32_e32 v172, v50, v117
	v_add_f32_e32 v173, v107, v118
	v_mul_f32_e32 v172, 0xbfb8aa3b, v172
	v_mul_f32_e32 v173, 0xbfb8aa3b, v173
	v_exp_f32_e32 v172, v172
	v_exp_f32_e32 v173, v173
	ds_write_b32 v167, v171 offset:0
	v_add_f32_e32 v172, 1.0, v172
	v_add_f32_e32 v173, 1.0, v173
	v_rcp_f32_e32 v172, v172
	v_rcp_f32_e32 v173, v173
	v_mul_f32_e32 v124, v170, v120
	v_mul_f32_e32 v173, 0xbf1b4598, v173
	v_add_f32_e32 v174, -1.0, v172
	v_mul_f32_e32 v173, 0x3fb8aa3b, v173
	v_fma_f32 v174, v121, v174, 1.0
	v_exp_f32_e32 v173, v173
	v_mul_f32_e32 v174, v170, v174
	v_mul_f32_e32 v150, v124, v124
	v_mul_f32_e32 v175, v169, v174
	v_mul_f32_e32 v141, v140, v173
	v_mul_f32_e32 v158, v122, v175
	v_rcp_f32_e32 v176, v141
	v_mul_f32_e32 v169, v169, v141
	v_mul_f32_e32 v174, v174, v176
	v_mul_f32_e32 v132, v172, v176
	ds_write_b32 v166, v169 offset:17408
	ds_write_b32 v166, v174 offset:52224
	v_sub_f32_e32 v169, v44, v1
	v_sub_f32_e32 v170, v46, v45
	v_sub_f32_e32 v171, v48, v47
	v_fma_f32 v169, v169, v115, v1
	v_fma_f32 v170, v170, v116, v45
	v_fma_f32 v171, v171, v119, v47
	v_add_f32_e32 v172, v51, v117
	v_add_f32_e32 v173, v108, v118
	v_mul_f32_e32 v172, 0xbfb8aa3b, v172
	v_mul_f32_e32 v173, 0xbfb8aa3b, v173
	v_exp_f32_e32 v172, v172
	v_exp_f32_e32 v173, v173
	ds_write_b32 v167, v171 offset:256
	v_add_f32_e32 v172, 1.0, v172
	v_add_f32_e32 v173, 1.0, v173
	v_rcp_f32_e32 v172, v172
	v_rcp_f32_e32 v173, v173
	v_mul_f32_e32 v125, v170, v120
	v_mul_f32_e32 v173, 0xbf1b4598, v173
	v_add_f32_e32 v174, -1.0, v172
	v_mul_f32_e32 v173, 0x3fb8aa3b, v173
	v_fma_f32 v174, v121, v174, 1.0
	v_exp_f32_e32 v173, v173
	v_mul_f32_e32 v174, v170, v174
	v_mul_f32_e32 v152, v125, v125
	v_mul_f32_e32 v175, v169, v174
	v_mul_f32_e32 v142, v141, v173
	v_mul_f32_e32 v160, v122, v175
	v_rcp_f32_e32 v176, v142
	v_mul_f32_e32 v169, v169, v142
	v_mul_f32_e32 v174, v174, v176
	v_mul_f32_e32 v133, v172, v176
	ds_write_b32 v166, v169 offset:17680
	ds_write_b32 v166, v174 offset:52496
	v_sub_f32_e32 v169, v1, v52
	v_sub_f32_e32 v170, v45, v54
	v_sub_f32_e32 v171, v47, v56
	v_fma_f32 v169, v169, v115, v52
	v_fma_f32 v170, v170, v116, v54
	v_fma_f32 v171, v171, v119, v56
	v_add_f32_e32 v172, v58, v117
	v_add_f32_e32 v173, v109, v118
	v_mul_f32_e32 v172, 0xbfb8aa3b, v172
	v_mul_f32_e32 v173, 0xbfb8aa3b, v173
	v_exp_f32_e32 v172, v172
	v_exp_f32_e32 v173, v173
	ds_write_b32 v167, v171 offset:512
	v_add_f32_e32 v172, 1.0, v172
	v_add_f32_e32 v173, 1.0, v173
	v_rcp_f32_e32 v172, v172
	v_rcp_f32_e32 v173, v173
	v_mul_f32_e32 v126, v170, v120
	v_mul_f32_e32 v173, 0xbf1b4598, v173
	v_add_f32_e32 v174, -1.0, v172
	v_mul_f32_e32 v173, 0x3fb8aa3b, v173
	v_fma_f32 v174, v121, v174, 1.0
	v_exp_f32_e32 v173, v173
	v_mul_f32_e32 v174, v170, v174
	v_mul_f32_e32 v151, v126, v126
	v_mul_f32_e32 v175, v169, v174
	v_mul_f32_e32 v143, v142, v173
	v_mul_f32_e32 v159, v122, v175
	v_rcp_f32_e32 v176, v143
	v_mul_f32_e32 v169, v169, v143
	v_mul_f32_e32 v174, v174, v176
	v_mul_f32_e32 v134, v172, v176
	ds_write_b32 v166, v169 offset:17952
	ds_write_b32 v166, v174 offset:52768
	v_sub_f32_e32 v169, v52, v49
	v_sub_f32_e32 v170, v54, v53
	v_sub_f32_e32 v171, v56, v55
	v_fma_f32 v169, v169, v115, v49
	v_fma_f32 v170, v170, v116, v53
	v_fma_f32 v171, v171, v119, v55
	v_add_f32_e32 v172, v57, v117
	v_add_f32_e32 v173, v110, v118
	v_mul_f32_e32 v172, 0xbfb8aa3b, v172
	v_mul_f32_e32 v173, 0xbfb8aa3b, v173
	v_exp_f32_e32 v172, v172
	v_exp_f32_e32 v173, v173
	ds_write_b32 v167, v171 offset:768
	v_add_f32_e32 v172, 1.0, v172
	v_add_f32_e32 v173, 1.0, v173
	v_rcp_f32_e32 v172, v172
	v_rcp_f32_e32 v173, v173
	v_mul_f32_e32 v127, v170, v120
	v_mul_f32_e32 v173, 0xbf1b4598, v173
	v_add_f32_e32 v174, -1.0, v172
	v_mul_f32_e32 v173, 0x3fb8aa3b, v173
	v_fma_f32 v174, v121, v174, 1.0
	v_exp_f32_e32 v173, v173
	v_mul_f32_e32 v174, v170, v174
	v_mul_f32_e32 v153, v127, v127
	v_mul_f32_e32 v175, v169, v174
	v_mul_f32_e32 v144, v143, v173
	v_mul_f32_e32 v161, v122, v175
	v_rcp_f32_e32 v176, v144
	v_mul_f32_e32 v169, v169, v144
	v_mul_f32_e32 v174, v174, v176
	v_mul_f32_e32 v135, v172, v176
	ds_write_b32 v166, v169 offset:18224
	ds_write_b32 v166, v174 offset:53040
	v_sub_f32_e32 v169, v49, v60
	v_sub_f32_e32 v170, v53, v62
	v_sub_f32_e32 v171, v55, v64
	v_fma_f32 v169, v169, v115, v60
	v_fma_f32 v170, v170, v116, v62
	v_fma_f32 v171, v171, v119, v64
	v_add_f32_e32 v172, v66, v117
	v_add_f32_e32 v173, v111, v118
	v_mul_f32_e32 v172, 0xbfb8aa3b, v172
	v_mul_f32_e32 v173, 0xbfb8aa3b, v173
	v_exp_f32_e32 v172, v172
	v_exp_f32_e32 v173, v173
	ds_write_b32 v167, v171 offset:1024
	v_add_f32_e32 v172, 1.0, v172
	v_add_f32_e32 v173, 1.0, v173
	v_rcp_f32_e32 v172, v172
	v_rcp_f32_e32 v173, v173
	v_mul_f32_e32 v128, v170, v120
	v_mul_f32_e32 v173, 0xbf1b4598, v173
	v_add_f32_e32 v174, -1.0, v172
	v_mul_f32_e32 v173, 0x3fb8aa3b, v173
	v_fma_f32 v174, v121, v174, 1.0
	v_exp_f32_e32 v173, v173
	v_mul_f32_e32 v174, v170, v174
	v_mul_f32_e32 v154, v128, v128
	v_mul_f32_e32 v175, v169, v174
	v_mul_f32_e32 v145, v144, v173
	v_mul_f32_e32 v162, v122, v175
	v_rcp_f32_e32 v176, v145
	v_mul_f32_e32 v169, v169, v145
	v_mul_f32_e32 v174, v174, v176
	v_mul_f32_e32 v136, v172, v176
	ds_write_b32 v166, v169 offset:18496
	ds_write_b32 v166, v174 offset:53312
	v_sub_f32_e32 v169, v60, v59
	v_sub_f32_e32 v170, v62, v61
	v_sub_f32_e32 v171, v64, v63
	v_fma_f32 v169, v169, v115, v59
	v_fma_f32 v170, v170, v116, v61
	v_fma_f32 v171, v171, v119, v63
	v_add_f32_e32 v172, v65, v117
	v_add_f32_e32 v173, v112, v118
	v_mul_f32_e32 v172, 0xbfb8aa3b, v172
	v_mul_f32_e32 v173, 0xbfb8aa3b, v173
	v_exp_f32_e32 v172, v172
	v_exp_f32_e32 v173, v173
	ds_write_b32 v167, v171 offset:1280
	v_add_f32_e32 v172, 1.0, v172
	v_add_f32_e32 v173, 1.0, v173
	v_rcp_f32_e32 v172, v172
	v_rcp_f32_e32 v173, v173
	v_mul_f32_e32 v129, v170, v120
	v_mul_f32_e32 v173, 0xbf1b4598, v173
	v_add_f32_e32 v174, -1.0, v172
	v_mul_f32_e32 v173, 0x3fb8aa3b, v173
	v_fma_f32 v174, v121, v174, 1.0
	v_exp_f32_e32 v173, v173
	v_mul_f32_e32 v174, v170, v174
	v_mul_f32_e32 v156, v129, v129
	v_mul_f32_e32 v175, v169, v174
	v_mul_f32_e32 v146, v145, v173
	v_mul_f32_e32 v164, v122, v175
	v_rcp_f32_e32 v176, v146
	v_mul_f32_e32 v169, v169, v146
	v_mul_f32_e32 v174, v174, v176
	v_mul_f32_e32 v137, v172, v176
	ds_write_b32 v166, v169 offset:18768
	ds_write_b32 v166, v174 offset:53584
	v_sub_f32_e32 v169, v59, v67
	v_sub_f32_e32 v170, v61, v69
	v_sub_f32_e32 v171, v63, v71
	v_fma_f32 v169, v169, v115, v67
	v_fma_f32 v170, v170, v116, v69
	v_fma_f32 v171, v171, v119, v71
	v_add_f32_e32 v172, v74, v117
	v_add_f32_e32 v173, v113, v118
	v_mul_f32_e32 v172, 0xbfb8aa3b, v172
	v_mul_f32_e32 v173, 0xbfb8aa3b, v173
	v_exp_f32_e32 v172, v172
	v_exp_f32_e32 v173, v173
	ds_write_b32 v167, v171 offset:1536
	v_add_f32_e32 v172, 1.0, v172
	v_add_f32_e32 v173, 1.0, v173
	v_rcp_f32_e32 v172, v172
	v_rcp_f32_e32 v173, v173
	v_mul_f32_e32 v130, v170, v120
	v_mul_f32_e32 v173, 0xbf1b4598, v173
	v_add_f32_e32 v174, -1.0, v172
	v_mul_f32_e32 v173, 0x3fb8aa3b, v173
	v_fma_f32 v174, v121, v174, 1.0
	v_exp_f32_e32 v173, v173
	v_mul_f32_e32 v174, v170, v174
	v_mul_f32_e32 v155, v130, v130
	v_mul_f32_e32 v175, v169, v174
	v_mul_f32_e32 v147, v146, v173
	v_mul_f32_e32 v163, v122, v175
	v_rcp_f32_e32 v176, v147
	v_mul_f32_e32 v169, v169, v147
	v_mul_f32_e32 v174, v174, v176
	v_mul_f32_e32 v138, v172, v176
	ds_write_b32 v166, v169 offset:19040
	ds_write_b32 v166, v174 offset:53856
	v_sub_f32_e32 v169, v67, v68
	v_sub_f32_e32 v170, v69, v70
	v_sub_f32_e32 v171, v71, v72
	v_fma_f32 v169, v169, v115, v68
	v_fma_f32 v170, v170, v116, v70
	v_fma_f32 v171, v171, v119, v72
	v_add_f32_e32 v172, v73, v117
	v_add_f32_e32 v173, v114, v118
	v_mul_f32_e32 v172, 0xbfb8aa3b, v172
	v_mul_f32_e32 v173, 0xbfb8aa3b, v173
	v_exp_f32_e32 v172, v172
	v_exp_f32_e32 v173, v173
	ds_write_b32 v167, v171 offset:1792
	v_add_f32_e32 v172, 1.0, v172
	v_add_f32_e32 v173, 1.0, v173
	v_rcp_f32_e32 v172, v172
	v_rcp_f32_e32 v173, v173
	v_mul_f32_e32 v131, v170, v120
	v_mul_f32_e32 v173, 0xbf1b4598, v173
	v_add_f32_e32 v174, -1.0, v172
	v_mul_f32_e32 v173, 0x3fb8aa3b, v173
	v_fma_f32 v174, v121, v174, 1.0
	v_exp_f32_e32 v173, v173
	v_mul_f32_e32 v174, v170, v174
	v_mul_f32_e32 v157, v131, v131
	v_mul_f32_e32 v175, v169, v174
	v_mul_f32_e32 v148, v147, v173
	v_mul_f32_e32 v165, v122, v175
	v_rcp_f32_e32 v176, v148
	v_mul_f32_e32 v169, v169, v148
	v_mul_f32_e32 v174, v174, v176
	v_mul_f32_e32 v139, v172, v176
	ds_write_b32 v166, v169 offset:19312
	ds_write_b32 v166, v174 offset:54128
	v_permlane32_swap_b32_e32 v150, v151
	v_permlane32_swap_b32_e32 v152, v153
	v_permlane32_swap_b32_e32 v154, v155
	v_permlane32_swap_b32_e32 v156, v157
	v_permlane32_swap_b32_e32 v158, v159
	v_permlane32_swap_b32_e32 v160, v161
	v_permlane32_swap_b32_e32 v162, v163
	v_permlane32_swap_b32_e32 v164, v165
	v_add_f32_e32 v182, v150, v151
	v_add_f32_e32 v183, v152, v153
	v_add_f32_e32 v184, v154, v155
	v_add_f32_e32 v185, v156, v157
	v_add_f32_e32 v186, v158, v159
	v_add_f32_e32 v187, v160, v161
	v_add_f32_e32 v188, v162, v163
	v_add_f32_e32 v189, v164, v165
	v_permlane16_swap_b32_e32 v182, v183
	v_permlane16_swap_b32_e32 v184, v185
	v_permlane16_swap_b32_e32 v186, v187
	v_permlane16_swap_b32_e32 v188, v189
	v_add_f32_e32 v190, v182, v183
	v_add_f32_e32 v191, v184, v185
	v_add_f32_e32 v192, v186, v187
	v_add_f32_e32 v193, v188, v189
	v_add_f32_dpp v194, v190, v190 row_mirror row_mask:0xf bank_mask:0x3
	v_add_f32_dpp v194, v191, v191 row_mirror row_mask:0xf bank_mask:0xc
	v_add_f32_dpp v195, v192, v192 row_mirror row_mask:0xf bank_mask:0x3
	v_add_f32_dpp v195, v193, v193 row_mirror row_mask:0xf bank_mask:0xc
	v_add_f32_dpp v196, v194, v194 row_half_mirror row_mask:0xf bank_mask:0x5
	s_nop 0
	v_add_f32_dpp v196, v195, v195 row_half_mirror row_mask:0xf bank_mask:0xa
	s_nop 1
	v_add_f32_dpp v196, v196, v196 quad_perm:[1,0,3,2] row_mask:0xf bank_mask:0xf
	s_nop 1
	v_add_f32_dpp v196, v196, v196 quad_perm:[2,3,0,1] row_mask:0xf bank_mask:0xf
	v_add_f32_e32 v197, 0x2b8cbccc, v196
	v_lshrrev_b32_e32 v198, 4, v76
	v_rsq_f32_e32 v197, v197
	v_bfe_u32 v168, v76, 3, 1
	v_lshl_add_u32 v198, v168, 2, v198
	v_add_u32_e32 v198, v198, v26
	v_lshl_add_u32 v198, v198, 2, s16
	s_mov_b32 s4, 0x10101010
	s_mov_b32 s5, 0x10101010
	s_mov_b64 exec, s[4:5]
	ds_write_b32 v198, v196
	s_mov_b64 exec, -1
	v_readlane_b32 s0, v197, 0
	v_readlane_b32 s1, v197, 16
	v_readlane_b32 s3, v197, 32
	v_readlane_b32 s4, v197, 48
	v_mul_f32_e32 v124, s0, v124
	v_mul_f32_e32 v125, s1, v125
	v_mul_f32_e32 v126, s3, v126
	v_mul_f32_e32 v127, s4, v127
	v_mul_f32_e64 v169, v124, -v140
	v_mul_f32_e32 v132, v124, v132
	v_mul_f32_e64 v170, v125, -v141
	v_mul_f32_e32 v133, v125, v133
	v_mul_f32_e64 v171, v126, -v142
	v_mul_f32_e32 v134, v126, v134
	v_mul_f32_e64 v172, v127, -v143
	v_mul_f32_e32 v135, v127, v135
	ds_write_b32 v166, v169 offset:0
	ds_write_b32 v166, v132 offset:34816
	ds_write_b32 v166, v170 offset:272
	ds_write_b32 v166, v133 offset:35088
	ds_write_b32 v166, v171 offset:544
	ds_write_b32 v166, v134 offset:35360
	ds_write_b32 v166, v172 offset:816
	ds_write_b32 v166, v135 offset:35632
	v_readlane_b32 s0, v197, 8
	v_readlane_b32 s1, v197, 24
	v_readlane_b32 s3, v197, 40
	v_readlane_b32 s4, v197, 56
	v_mul_f32_e32 v128, s0, v128
	v_mul_f32_e32 v129, s1, v129
	v_mul_f32_e32 v130, s3, v130
	v_mul_f32_e32 v131, s4, v131
	v_mul_f32_e64 v169, v128, -v144
	v_mul_f32_e32 v136, v128, v136
	v_mul_f32_e64 v170, v129, -v145
	v_mul_f32_e32 v137, v129, v137
	v_mul_f32_e64 v171, v130, -v146
	v_mul_f32_e32 v138, v130, v138
	v_mul_f32_e64 v172, v131, -v147
	v_mul_f32_e32 v139, v131, v139
	ds_write_b32 v166, v169 offset:1088
	ds_write_b32 v166, v136 offset:35904
	ds_write_b32 v166, v170 offset:1360
	ds_write_b32 v166, v137 offset:36176
	ds_write_b32 v166, v171 offset:1632
	ds_write_b32 v166, v138 offset:36448
	ds_write_b32 v166, v172 offset:1904
	ds_write_b32 v166, v139 offset:36720
	v_lshlrev_b32_e32 v168, 8, v78
	v_lshl_add_u32 v168, v76, 2, v168
	v_add_u32_e32 v168, 0x11000, v168
	ds_write_b32 v168, v148
	ds_read_b128 v[136:139], v79 offset:0
	ds_read_b128 v[152:155], v79 offset:34816
	ds_read_b128 v[140:143], v79 offset:64
	ds_read_b128 v[156:159], v79 offset:34880
	ds_read_b128 v[144:147], v79 offset:128
	ds_read_b128 v[160:163], v79 offset:34944
	ds_read_b128 v[148:151], v79 offset:192
	ds_read_b128 v[164:167], v79 offset:35008
	v_cmp_ge_u32_e64 s[0:1], 1, v87
	v_cmp_ge_u32_e64 s[4:5], 2, v87
	v_cmp_ge_u32_e64 s[6:7], 3, v87
	v_cmp_ge_u32_e32 vcc, 0, v87
	s_waitcnt lgkmcnt(0)
	v_mfma_f32_16x16x4_f32 v[36:39], v136, v152, 0
	v_mfma_f32_16x16x4_f32 v[40:43], v137, v153, 0
	v_mfma_f32_16x16x4_f32 v[36:39], v138, v154, v[36:39]
	v_mfma_f32_16x16x4_f32 v[40:43], v139, v155, v[40:43]
	v_mfma_f32_16x16x4_f32 v[36:39], v140, v156, v[36:39]
	v_mfma_f32_16x16x4_f32 v[40:43], v141, v157, v[40:43]
	v_mfma_f32_16x16x4_f32 v[36:39], v142, v158, v[36:39]
	v_mfma_f32_16x16x4_f32 v[40:43], v143, v159, v[40:43]
	v_mfma_f32_16x16x4_f32 v[36:39], v144, v160, v[36:39]
	v_mfma_f32_16x16x4_f32 v[40:43], v145, v161, v[40:43]
	v_mfma_f32_16x16x4_f32 v[36:39], v146, v162, v[36:39]
	v_mfma_f32_16x16x4_f32 v[40:43], v147, v163, v[40:43]
	v_mfma_f32_16x16x4_f32 v[36:39], v148, v164, v[36:39]
	v_mfma_f32_16x16x4_f32 v[40:43], v149, v165, v[40:43]
	v_mfma_f32_16x16x4_f32 v[36:39], v150, v166, v[36:39]
	v_mfma_f32_16x16x4_f32 v[40:43], v151, v167, v[40:43]
	s_nop 7
	s_nop 2
	v_pk_add_f32 v[36:37], v[36:37], v[40:41]
	v_pk_add_f32 v[38:39], v[38:39], v[42:43]
	v_cndmask_b32_e32 v36, 0, v36, vcc
	v_cndmask_b32_e64 v37, 0, v37, s[0:1]
	v_cndmask_b32_e64 v38, 0, v38, s[4:5]
	v_cndmask_b32_e64 v39, 0, v39, s[6:7]
	ds_write_b32 v86, v36 offset:0
	ds_write_b32 v86, v37 offset:32
	ds_write_b32 v86, v38 offset:64
	ds_write_b32 v86, v39 offset:96
	ds_read_b128 v[124:127], v92 offset:32
	ds_read_b128 v[128:131], v92 offset:64
	ds_read_b128 v[132:135], v92 offset:96
	ds_read_b128 v[136:139], v92 offset:128
	ds_read_b128 v[144:147], v92 offset:160
	ds_read_b128 v[148:151], v92 offset:176
	ds_read_b128 v[152:155], v92 offset:192
	ds_read_b128 v[156:159], v92 offset:208
	ds_read_b128 v[160:163], v92 offset:224
	ds_read_b128 v[164:167], v92 offset:240
	ds_read_b128 v[182:185], v93 offset:512
	ds_read_b128 v[186:189], v93 offset:528
	ds_read_b128 v[190:193], v93 offset:544
	ds_read_b128 v[194:197], v93 offset:560
	v_cmp_eq_u32_e32 vcc, 0, v102
	v_cndmask_b32_e32 v36, 0, v103, vcc
	v_cmp_eq_u32_e32 vcc, 1, v102
	v_cndmask_b32_e32 v37, 0, v103, vcc
	v_cmp_eq_u32_e32 vcc, 2, v102
	v_cndmask_b32_e32 v38, 0, v103, vcc
	v_cmp_eq_u32_e32 vcc, 3, v102
	v_cndmask_b32_e32 v39, 0, v103, vcc
	v_cmp_eq_u32_e32 vcc, 4, v102
	v_cndmask_b32_e32 v40, 0, v103, vcc
	v_cmp_eq_u32_e32 vcc, 5, v102
	v_cndmask_b32_e32 v41, 0, v103, vcc
	v_cmp_eq_u32_e32 vcc, 6, v102
	v_cndmask_b32_e32 v42, 0, v103, vcc
	v_cmp_eq_u32_e32 vcc, 7, v102
	v_cndmask_b32_e32 v43, 0, v103, vcc
	s_waitcnt lgkmcnt(0)
	v_fmac_f32_e32 v37, v124, v36
	v_fmac_f32_e32 v38, v128, v36
	v_fmac_f32_e32 v39, v132, v36
	v_fmac_f32_e32 v40, v136, v36
	v_fmac_f32_e32 v41, v144, v36
	v_fmac_f32_e32 v42, v152, v36
	v_fmac_f32_e32 v43, v160, v36
	v_fmac_f32_e32 v38, v129, v37
	v_fmac_f32_e32 v39, v133, v37
	v_fmac_f32_e32 v40, v137, v37
	v_fmac_f32_e32 v41, v145, v37
	v_fmac_f32_e32 v42, v153, v37
	v_fmac_f32_e32 v43, v161, v37
	v_fmac_f32_e32 v39, v134, v38
	v_fmac_f32_e32 v40, v138, v38
	v_fmac_f32_e32 v41, v146, v38
	v_fmac_f32_e32 v42, v154, v38
	v_fmac_f32_e32 v43, v162, v38
	v_fmac_f32_e32 v40, v139, v39
	v_fmac_f32_e32 v41, v147, v39
	v_fmac_f32_e32 v42, v155, v39
	v_fmac_f32_e32 v43, v163, v39
	v_fmac_f32_e32 v41, v148, v40
	v_fmac_f32_e32 v42, v156, v40
	v_fmac_f32_e32 v43, v164, v40
	v_fmac_f32_e32 v42, v157, v41
	v_fmac_f32_e32 v43, v165, v41
	v_fmac_f32_e32 v43, v166, v42
	v_mul_f32_e32 v44, v182, v36
	v_fmac_f32_e32 v44, v183, v37
	v_fmac_f32_e32 v44, v184, v38
	v_fmac_f32_e32 v44, v185, v39
	v_fmac_f32_e32 v44, v186, v40
	v_fmac_f32_e32 v44, v187, v41
	v_fmac_f32_e32 v44, v188, v42
	v_fmac_f32_e32 v44, v189, v43
	v_mul_f32_e32 v45, v190, v36
	v_fmac_f32_e32 v45, v191, v37
	v_fmac_f32_e32 v45, v192, v38
	v_fmac_f32_e32 v45, v193, v39
	v_fmac_f32_e32 v45, v194, v40
	v_fmac_f32_e32 v45, v195, v41
	v_fmac_f32_e32 v45, v196, v42
	v_fmac_f32_e32 v45, v197, v43
	ds_write_b32 v100, v36 offset:0
	ds_write_b32 v100, v37 offset:32
	ds_write_b32 v100, v38 offset:64
	ds_write_b32 v100, v39 offset:96
	ds_write_b32 v100, v40 offset:128
	ds_write_b32 v100, v41 offset:160
	ds_write_b32 v100, v42 offset:192
	ds_write_b32 v100, v43 offset:224
	ds_write_b32 v101, v44 offset:512
	ds_write_b32 v101, v45 offset:544
	s_lshl_b32 s17, s40, 6
	s_cmp_lg_u32 s40, 31
	s_waitcnt lgkmcnt(0)
	s_barrier
	s_cbranch_scc0 .LBB0_586
	v_readfirstlane_b32 s0, v180
	s_nop 1
	s_cmpk_ge_u32 s0, 0x100
	s_cbranch_scc1 .LBB0_586
	s_add_i32 s3, s17, 64
	s_add_u32 s0, s80, s3
	s_addc_u32 s1, s81, 0
	v_ashrrev_i32_e32 v27, 31, v26
	v_lshl_add_u64 v[4:5], s[0:1], 0, v[26:27]
	v_mad_u64_u32 v[2:3], s[0:1], v4, s83, 0
	v_mad_i32_i24 v3, v5, s83, v3
	v_add_u32_e32 v1, s3, v26
	v_mov_b32_e32 v95, v94
	v_lshl_add_u64 v[2:3], s[46:47], 0, v[2:3]
	v_cmp_lt_i32_e32 vcc, 0, v1
	v_mov_b32_e32 v106, 0
	v_lshl_add_u64 v[2:3], v[28:29], 1, v[2:3]
	v_mov_b64_e32 v[34:35], v[94:95]
	s_and_saveexec_b64 s[0:1], vcc
	s_cbranch_execz .LBB0_585
	global_load_ushort v52, v[2:3], off offset:-3072
	global_load_ushort v53, v[2:3], off offset:-2048
	global_load_ushort v54, v[2:3], off offset:-1024

.LBB0_586:
.Lrw_entry:
	v_readfirstlane_b32 s0, v180
	s_nop 1
	s_cmpk_ge_u32 s0, 0x100
	s_cbranch_scc1 .Lrw_epi
	v_and_b32_e32 v222, 15, v180
	v_bfe_u32 v223, v180, 4, 2
	v_lshrrev_b32_e32 v240, 6, v180
	v_lshrrev_b32_e32 v176, 2, v222
	v_and_b32_e32 v177, 1, v222
	v_lshl_add_u32 v176, v177, 2, v176
	v_lshlrev_b32_e32 v171, 5, v176
	v_mul_u32_u24_e32 v176, 0x110, v176
	v_and_b32_e32 v177, 2, v222
	v_lshl_add_u32 v171, v177, 8, v171
	v_lshl_add_u32 v171, v223, 2, v171
	v_add_u32_e32 v171, 0x15800, v171
	v_mul_u32_u24_e32 v177, 0x2200, v177
	v_lshl_add_u32 v168, v223, 4, v176
	v_add_u32_e32 v168, v168, v177
	v_lshlrev_b32_e32 v178, 6, v240
	v_lshl_add_u32 v178, v222, 2, v178
	v_lshl_add_u32 v178, v223, 8, v178
	v_add_u32_e32 v169, s41, v178
	v_add_u32_e32 v175, 0x1f800, v178
	v_mul_u32_u24_e32 v176, 0x110, v223
	v_lshl_add_u32 v173, v222, 2, v176
	v_add_u32_e32 v173, 0x8800, v173
	v_add_u32_e32 v2, 0x440, v173
	v_add_u32_e32 v3, 0x4400, v173
	v_add_u32_e32 v5, 0x4840, v173
	v_lshlrev_b32_e32 v174, 4, v223
	v_add_u32_e32 v174, 0x11000, v174
	s_mov_b32 s14, 0
	s_mov_b32 s15, 1
	v_mov_b32_e32 v179, 0x27f00
	v_mov_b32_e32 v241, 1
	v_mov_b32_e32 v80, 0
	v_mov_b32_e32 v81, 0
	ds_read_b128 v[44:47], v168 offset:0
	ds_read_b128 v[48:51], v168 offset:64
	ds_read_b128 v[68:71], v168 offset:128
	ds_read_b128 v[96:99], v168 offset:192
	ds_read_b32 v216, v171 offset:256
	ds_read_b32 v217, v171 offset:272
	ds_read_b32 v214, v169 offset:0
	ds_read_b32 v215, v169 offset:1024
	ds_read_b32 v218, v171 offset:0
	ds_read_b32 v219, v171 offset:16
	ds_read2_b32 v[182:183], v173 offset0:0 offset1:16
	ds_read2_b32 v[184:185], v173 offset0:32 offset1:48
	ds_read2_b32 v[186:187], v2 offset0:0 offset1:16
	ds_read2_b32 v[188:189], v2 offset0:32 offset1:48
	ds_read2_b32 v[190:191], v3 offset0:0 offset1:16
	ds_read2_b32 v[192:193], v3 offset0:32 offset1:48
	ds_read2_b32 v[194:195], v5 offset0:0 offset1:16
	ds_read2_b32 v[196:197], v5 offset0:32 offset1:48
	s_mov_b32 s1, 0
	s_waitcnt lgkmcnt(0)
	v_mfma_f32_16x16x4_f32 v[36:39], v44, v224, 0
	v_mfma_f32_16x16x4_f32 v[40:43], v45, v225, 0
	v_mfma_f32_16x16x4_f32 v[36:39], v46, v226, v[36:39]
	v_mfma_f32_16x16x4_f32 v[40:43], v47, v227, v[40:43]
	v_mfma_f32_16x16x4_f32 v[36:39], v48, v228, v[36:39]
	v_mfma_f32_16x16x4_f32 v[40:43], v49, v229, v[40:43]
	v_mfma_f32_16x16x4_f32 v[36:39], v50, v230, v[36:39]
	v_mfma_f32_16x16x4_f32 v[40:43], v51, v231, v[40:43]
	v_mfma_f32_16x16x4_f32 v[36:39], v68, v232, v[36:39]
	v_mfma_f32_16x16x4_f32 v[40:43], v69, v233, v[40:43]
	v_mfma_f32_16x16x4_f32 v[36:39], v70, v234, v[36:39]
	v_mfma_f32_16x16x4_f32 v[40:43], v71, v235, v[40:43]
	v_mfma_f32_16x16x4_f32 v[36:39], v96, v236, v[36:39]
	v_mfma_f32_16x16x4_f32 v[40:43], v97, v237, v[40:43]
	v_mfma_f32_16x16x4_f32 v[36:39], v98, v238, v[36:39]
	v_mfma_f32_16x16x4_f32 v[40:43], v99, v239, v[40:43]
	v_mfma_f32_16x16x4_f32 v[36:39], v216, v214, v[36:39]
	v_mfma_f32_16x16x4_f32 v[40:43], v217, v215, v[40:43]
	v_mfma_f32_16x16x4_f32 v[224:227], v190, v214, v[224:227]
	v_mfma_f32_16x16x4_f32 v[228:231], v191, v214, v[228:231]
	v_mfma_f32_16x16x4_f32 v[232:235], v192, v214, v[232:235]
	v_mfma_f32_16x16x4_f32 v[236:239], v193, v214, v[236:239]
	ds_read_b128 v[44:47], v168 offset:2176
	ds_read_b128 v[48:51], v168 offset:2240
	ds_read_b128 v[68:71], v168 offset:2304
	ds_read_b128 v[96:99], v168 offset:2368
	ds_read_b32 v216, v171 offset:1280
	ds_read_b32 v217, v171 offset:1296
	v_pk_add_f32 v[84:85], v[36:37], v[40:41]
	v_pk_add_f32 v[82:83], v[38:39], v[42:43]
	s_nop 1
	v_mfma_f32_16x16x4_f32 v[88:91], v218, v84, v[80:83]
	v_mfma_f32_16x16x4_f32 v[88:91], v219, v85, v[88:91]
	v_mfma_f32_16x16x4_f32 v[224:227], v194, v215, v[224:227]
	v_mfma_f32_16x16x4_f32 v[228:231], v195, v215, v[228:231]
	v_mfma_f32_16x16x4_f32 v[232:235], v196, v215, v[232:235]
	v_mfma_f32_16x16x4_f32 v[236:239], v197, v215, v[236:239]
	ds_read_b128 v[198:201], v174 offset:0
	ds_read_b128 v[202:205], v174 offset:64
	ds_read_b128 v[206:209], v174 offset:128
	ds_read_b128 v[210:213], v174 offset:192
	ds_read_b32 v218, v171 offset:1024
	ds_read_b32 v219, v171 offset:1040
	ds_read_b32 v214, v169 offset:2048
	ds_read_b32 v215, v169 offset:3072
	v_mfma_f32_16x16x4_f32 v[224:227], v182, v88, v[224:227]
	v_mfma_f32_16x16x4_f32 v[228:231], v183, v88, v[228:231]
	v_mfma_f32_16x16x4_f32 v[232:235], v184, v88, v[232:235]
	v_mfma_f32_16x16x4_f32 v[236:239], v185, v88, v[236:239]
	v_mfma_f32_16x16x4_f32 v[224:227], v186, v89, v[224:227]
	v_mfma_f32_16x16x4_f32 v[228:231], v187, v89, v[228:231]
	v_mfma_f32_16x16x4_f32 v[232:235], v188, v89, v[232:235]
	v_mfma_f32_16x16x4_f32 v[236:239], v189, v89, v[236:239]
	v_add_u32_e32 v173, 0x880, v173
	v_add_u32_e32 v2, 0x880, v2
	v_add_u32_e32 v3, 0x880, v3
	v_add_u32_e32 v5, 0x880, v5
	ds_read2_b32 v[182:183], v173 offset0:0 offset1:16
	ds_read2_b32 v[184:185], v173 offset0:32 offset1:48
	ds_read2_b32 v[186:187], v2 offset0:0 offset1:16
	ds_read2_b32 v[188:189], v2 offset0:32 offset1:48
	ds_read2_b32 v[190:191], v3 offset0:0 offset1:16
	ds_read2_b32 v[192:193], v3 offset0:32 offset1:48
	ds_read2_b32 v[194:195], v5 offset0:0 offset1:16
	ds_read2_b32 v[196:197], v5 offset0:32 offset1:48
	ds_write2st64_b32 v175, v90, v91 offset0:0 offset1:4
	s_mov_b64 exec, s[14:15]
	ds_add_u32 v179, v241 offset:0
	s_mov_b64 exec, -1
	s_waitcnt lgkmcnt(14)
	v_pk_mul_f32 v[224:225], v[224:225], v[198:199]
	v_pk_mul_f32 v[226:227], v[226:227], v[200:201]
	v_pk_mul_f32 v[228:229], v[228:229], v[202:203]
	v_pk_mul_f32 v[230:231], v[230:231], v[204:205]
	v_mfma_f32_16x16x4_f32 v[36:39], v44, v224, 0
	v_mfma_f32_16x16x4_f32 v[40:43], v45, v225, 0
	v_mfma_f32_16x16x4_f32 v[36:39], v46, v226, v[36:39]
	v_mfma_f32_16x16x4_f32 v[40:43], v47, v227, v[40:43]
	v_pk_mul_f32 v[232:233], v[232:233], v[206:207]
	v_pk_mul_f32 v[234:235], v[234:235], v[208:209]
	v_mfma_f32_16x16x4_f32 v[36:39], v48, v228, v[36:39]
	v_mfma_f32_16x16x4_f32 v[40:43], v49, v229, v[40:43]
	v_mfma_f32_16x16x4_f32 v[36:39], v50, v230, v[36:39]
	v_mfma_f32_16x16x4_f32 v[40:43], v51, v231, v[40:43]
	v_pk_mul_f32 v[236:237], v[236:237], v[210:211]
	v_pk_mul_f32 v[238:239], v[238:239], v[212:213]
	v_mfma_f32_16x16x4_f32 v[36:39], v68, v232, v[36:39]
	v_mfma_f32_16x16x4_f32 v[40:43], v69, v233, v[40:43]
	v_mfma_f32_16x16x4_f32 v[36:39], v70, v234, v[36:39]
	v_mfma_f32_16x16x4_f32 v[40:43], v71, v235, v[40:43]
	v_mfma_f32_16x16x4_f32 v[36:39], v96, v236, v[36:39]
	v_mfma_f32_16x16x4_f32 v[40:43], v97, v237, v[40:43]
	v_mfma_f32_16x16x4_f32 v[36:39], v98, v238, v[36:39]
	v_mfma_f32_16x16x4_f32 v[40:43], v99, v239, v[40:43]
	s_waitcnt lgkmcnt(2)
	v_mfma_f32_16x16x4_f32 v[36:39], v216, v214, v[36:39]
	v_mfma_f32_16x16x4_f32 v[40:43], v217, v215, v[40:43]
	v_mfma_f32_16x16x4_f32 v[224:227], v190, v214, v[224:227]
	v_mfma_f32_16x16x4_f32 v[228:231], v191, v214, v[228:231]
	v_mfma_f32_16x16x4_f32 v[232:235], v192, v214, v[232:235]
	v_mfma_f32_16x16x4_f32 v[236:239], v193, v214, v[236:239]
	ds_read_b128 v[44:47], v168 offset:4352
	ds_read_b128 v[48:51], v168 offset:4416
	ds_read_b128 v[68:71], v168 offset:4480
	ds_read_b128 v[96:99], v168 offset:4544
	ds_read_b32 v216, v171 offset:2304
	ds_read_b32 v217, v171 offset:2320
	v_pk_add_f32 v[84:85], v[36:37], v[40:41]
	v_pk_add_f32 v[82:83], v[38:39], v[42:43]
	s_nop 1
	v_mfma_f32_16x16x4_f32 v[88:91], v218, v84, v[80:83]
	v_mfma_f32_16x16x4_f32 v[88:91], v219, v85, v[88:91]
	v_mfma_f32_16x16x4_f32 v[224:227], v194, v215, v[224:227]
	v_mfma_f32_16x16x4_f32 v[228:231], v195, v215, v[228:231]
	v_mfma_f32_16x16x4_f32 v[232:235], v196, v215, v[232:235]
	v_mfma_f32_16x16x4_f32 v[236:239], v197, v215, v[236:239]
	ds_read_b128 v[198:201], v174 offset:256
	ds_read_b128 v[202:205], v174 offset:320
	ds_read_b128 v[206:209], v174 offset:384
	ds_read_b128 v[210:213], v174 offset:448
	ds_read_b32 v218, v171 offset:2048
	ds_read_b32 v219, v171 offset:2064
	ds_read_b32 v214, v169 offset:4096
	ds_read_b32 v215, v169 offset:5120
	v_mfma_f32_16x16x4_f32 v[224:227], v182, v88, v[224:227]
	v_mfma_f32_16x16x4_f32 v[228:231], v183, v88, v[228:231]
	v_mfma_f32_16x16x4_f32 v[232:235], v184, v88, v[232:235]
	v_mfma_f32_16x16x4_f32 v[236:239], v185, v88, v[236:239]
	v_mfma_f32_16x16x4_f32 v[224:227], v186, v89, v[224:227]
	v_mfma_f32_16x16x4_f32 v[228:231], v187, v89, v[228:231]
	v_mfma_f32_16x16x4_f32 v[232:235], v188, v89, v[232:235]
	v_mfma_f32_16x16x4_f32 v[236:239], v189, v89, v[236:239]
	v_add_u32_e32 v173, 0x880, v173
	v_add_u32_e32 v2, 0x880, v2
	v_add_u32_e32 v3, 0x880, v3
	v_add_u32_e32 v5, 0x880, v5
	ds_read2_b32 v[182:183], v173 offset0:0 offset1:16
	ds_read2_b32 v[184:185], v173 offset0:32 offset1:48
	ds_read2_b32 v[186:187], v2 offset0:0 offset1:16
	ds_read2_b32 v[188:189], v2 offset0:32 offset1:48
	ds_read2_b32 v[190:191], v3 offset0:0 offset1:16
	ds_read2_b32 v[192:193], v3 offset0:32 offset1:48
	ds_read2_b32 v[194:195], v5 offset0:0 offset1:16
	ds_read2_b32 v[196:197], v5 offset0:32 offset1:48
	ds_write2st64_b32 v175, v90, v91 offset0:8 offset1:12
	s_mov_b64 exec, s[14:15]
	ds_add_u32 v179, v241 offset:4
	s_mov_b64 exec, -1
	s_waitcnt lgkmcnt(14)
	v_pk_mul_f32 v[224:225], v[224:225], v[198:199]
	v_pk_mul_f32 v[226:227], v[226:227], v[200:201]
	v_pk_mul_f32 v[228:229], v[228:229], v[202:203]
	v_pk_mul_f32 v[230:231], v[230:231], v[204:205]
	v_mfma_f32_16x16x4_f32 v[36:39], v44, v224, 0
	v_mfma_f32_16x16x4_f32 v[40:43], v45, v225, 0
	v_mfma_f32_16x16x4_f32 v[36:39], v46, v226, v[36:39]
	v_mfma_f32_16x16x4_f32 v[40:43], v47, v227, v[40:43]
	v_pk_mul_f32 v[232:233], v[232:233], v[206:207]
	v_pk_mul_f32 v[234:235], v[234:235], v[208:209]
	v_mfma_f32_16x16x4_f32 v[36:39], v48, v228, v[36:39]
	v_mfma_f32_16x16x4_f32 v[40:43], v49, v229, v[40:43]
	v_mfma_f32_16x16x4_f32 v[36:39], v50, v230, v[36:39]
	v_mfma_f32_16x16x4_f32 v[40:43], v51, v231, v[40:43]
	v_pk_mul_f32 v[236:237], v[236:237], v[210:211]
	v_pk_mul_f32 v[238:239], v[238:239], v[212:213]
	v_mfma_f32_16x16x4_f32 v[36:39], v68, v232, v[36:39]
	v_mfma_f32_16x16x4_f32 v[40:43], v69, v233, v[40:43]
	v_mfma_f32_16x16x4_f32 v[36:39], v70, v234, v[36:39]
	v_mfma_f32_16x16x4_f32 v[40:43], v71, v235, v[40:43]
	v_mfma_f32_16x16x4_f32 v[36:39], v96, v236, v[36:39]
	v_mfma_f32_16x16x4_f32 v[40:43], v97, v237, v[40:43]
	v_mfma_f32_16x16x4_f32 v[36:39], v98, v238, v[36:39]
	v_mfma_f32_16x16x4_f32 v[40:43], v99, v239, v[40:43]
	s_waitcnt lgkmcnt(2)
	v_mfma_f32_16x16x4_f32 v[36:39], v216, v214, v[36:39]
	v_mfma_f32_16x16x4_f32 v[40:43], v217, v215, v[40:43]
	v_mfma_f32_16x16x4_f32 v[224:227], v190, v214, v[224:227]
	v_mfma_f32_16x16x4_f32 v[228:231], v191, v214, v[228:231]
	v_mfma_f32_16x16x4_f32 v[232:235], v192, v214, v[232:235]
	v_mfma_f32_16x16x4_f32 v[236:239], v193, v214, v[236:239]
	ds_read_b128 v[44:47], v168 offset:6528
	ds_read_b128 v[48:51], v168 offset:6592
	ds_read_b128 v[68:71], v168 offset:6656
	ds_read_b128 v[96:99], v168 offset:6720
	ds_read_b32 v216, v171 offset:3328
	ds_read_b32 v217, v171 offset:3344
	v_pk_add_f32 v[84:85], v[36:37], v[40:41]
	v_pk_add_f32 v[82:83], v[38:39], v[42:43]
	s_nop 1
	v_mfma_f32_16x16x4_f32 v[88:91], v218, v84, v[80:83]
	v_mfma_f32_16x16x4_f32 v[88:91], v219, v85, v[88:91]
	v_mfma_f32_16x16x4_f32 v[224:227], v194, v215, v[224:227]
	v_mfma_f32_16x16x4_f32 v[228:231], v195, v215, v[228:231]
	v_mfma_f32_16x16x4_f32 v[232:235], v196, v215, v[232:235]
	v_mfma_f32_16x16x4_f32 v[236:239], v197, v215, v[236:239]
	ds_read_b128 v[198:201], v174 offset:512
	ds_read_b128 v[202:205], v174 offset:576
	ds_read_b128 v[206:209], v174 offset:640
	ds_read_b128 v[210:213], v174 offset:704
	ds_read_b32 v218, v171 offset:3072
	ds_read_b32 v219, v171 offset:3088
	ds_read_b32 v214, v169 offset:6144
	ds_read_b32 v215, v169 offset:7168
	v_mfma_f32_16x16x4_f32 v[224:227], v182, v88, v[224:227]
	v_mfma_f32_16x16x4_f32 v[228:231], v183, v88, v[228:231]
	v_mfma_f32_16x16x4_f32 v[232:235], v184, v88, v[232:235]
	v_mfma_f32_16x16x4_f32 v[236:239], v185, v88, v[236:239]
	v_mfma_f32_16x16x4_f32 v[224:227], v186, v89, v[224:227]
	v_mfma_f32_16x16x4_f32 v[228:231], v187, v89, v[228:231]
	v_mfma_f32_16x16x4_f32 v[232:235], v188, v89, v[232:235]
	v_mfma_f32_16x16x4_f32 v[236:239], v189, v89, v[236:239]
	v_add_u32_e32 v173, 0x880, v173
	v_add_u32_e32 v2, 0x880, v2
	v_add_u32_e32 v3, 0x880, v3
	v_add_u32_e32 v5, 0x880, v5
	ds_read2_b32 v[182:183], v173 offset0:0 offset1:16
	ds_read2_b32 v[184:185], v173 offset0:32 offset1:48
	ds_read2_b32 v[186:187], v2 offset0:0 offset1:16
	ds_read2_b32 v[188:189], v2 offset0:32 offset1:48
	ds_read2_b32 v[190:191], v3 offset0:0 offset1:16
	ds_read2_b32 v[192:193], v3 offset0:32 offset1:48
	ds_read2_b32 v[194:195], v5 offset0:0 offset1:16
	ds_read2_b32 v[196:197], v5 offset0:32 offset1:48
	ds_write2st64_b32 v175, v90, v91 offset0:16 offset1:20
	s_mov_b64 exec, s[14:15]
	ds_add_u32 v179, v241 offset:8
	s_mov_b64 exec, -1
	s_waitcnt lgkmcnt(14)
	v_pk_mul_f32 v[224:225], v[224:225], v[198:199]
	v_pk_mul_f32 v[226:227], v[226:227], v[200:201]
	v_pk_mul_f32 v[228:229], v[228:229], v[202:203]
	v_pk_mul_f32 v[230:231], v[230:231], v[204:205]
	v_mfma_f32_16x16x4_f32 v[36:39], v44, v224, 0
	v_mfma_f32_16x16x4_f32 v[40:43], v45, v225, 0
	v_mfma_f32_16x16x4_f32 v[36:39], v46, v226, v[36:39]
	v_mfma_f32_16x16x4_f32 v[40:43], v47, v227, v[40:43]
	v_pk_mul_f32 v[232:233], v[232:233], v[206:207]
	v_pk_mul_f32 v[234:235], v[234:235], v[208:209]
	v_mfma_f32_16x16x4_f32 v[36:39], v48, v228, v[36:39]
	v_mfma_f32_16x16x4_f32 v[40:43], v49, v229, v[40:43]
	v_mfma_f32_16x16x4_f32 v[36:39], v50, v230, v[36:39]
	v_mfma_f32_16x16x4_f32 v[40:43], v51, v231, v[40:43]
	v_pk_mul_f32 v[236:237], v[236:237], v[210:211]
	v_pk_mul_f32 v[238:239], v[238:239], v[212:213]
	v_mfma_f32_16x16x4_f32 v[36:39], v68, v232, v[36:39]
	v_mfma_f32_16x16x4_f32 v[40:43], v69, v233, v[40:43]
	v_mfma_f32_16x16x4_f32 v[36:39], v70, v234, v[36:39]
	v_mfma_f32_16x16x4_f32 v[40:43], v71, v235, v[40:43]
	v_mfma_f32_16x16x4_f32 v[36:39], v96, v236, v[36:39]
	v_mfma_f32_16x16x4_f32 v[40:43], v97, v237, v[40:43]
	v_mfma_f32_16x16x4_f32 v[36:39], v98, v238, v[36:39]
	v_mfma_f32_16x16x4_f32 v[40:43], v99, v239, v[40:43]
	s_waitcnt lgkmcnt(2)
	v_mfma_f32_16x16x4_f32 v[36:39], v216, v214, v[36:39]
	v_mfma_f32_16x16x4_f32 v[40:43], v217, v215, v[40:43]
	v_mfma_f32_16x16x4_f32 v[224:227], v190, v214, v[224:227]
	v_mfma_f32_16x16x4_f32 v[228:231], v191, v214, v[228:231]
	v_mfma_f32_16x16x4_f32 v[232:235], v192, v214, v[232:235]
	v_mfma_f32_16x16x4_f32 v[236:239], v193, v214, v[236:239]
	ds_read_b128 v[44:47], v168 offset:8704
	ds_read_b128 v[48:51], v168 offset:8768
	ds_read_b128 v[68:71], v168 offset:8832
	ds_read_b128 v[96:99], v168 offset:8896
	ds_read_b32 v216, v171 offset:4352
	ds_read_b32 v217, v171 offset:4368
	v_pk_add_f32 v[84:85], v[36:37], v[40:41]
	v_pk_add_f32 v[82:83], v[38:39], v[42:43]
	s_nop 1
	v_mfma_f32_16x16x4_f32 v[88:91], v218, v84, v[80:83]
	v_mfma_f32_16x16x4_f32 v[88:91], v219, v85, v[88:91]
	v_mfma_f32_16x16x4_f32 v[224:227], v194, v215, v[224:227]
	v_mfma_f32_16x16x4_f32 v[228:231], v195, v215, v[228:231]
	v_mfma_f32_16x16x4_f32 v[232:235], v196, v215, v[232:235]
	v_mfma_f32_16x16x4_f32 v[236:239], v197, v215, v[236:239]
	ds_read_b128 v[198:201], v174 offset:768
	ds_read_b128 v[202:205], v174 offset:832
	ds_read_b128 v[206:209], v174 offset:896
	ds_read_b128 v[210:213], v174 offset:960
	ds_read_b32 v218, v171 offset:4096
	ds_read_b32 v219, v171 offset:4112
	ds_read_b32 v214, v169 offset:8192
	ds_read_b32 v215, v169 offset:9216
	v_mfma_f32_16x16x4_f32 v[224:227], v182, v88, v[224:227]
	v_mfma_f32_16x16x4_f32 v[228:231], v183, v88, v[228:231]
	v_mfma_f32_16x16x4_f32 v[232:235], v184, v88, v[232:235]
	v_mfma_f32_16x16x4_f32 v[236:239], v185, v88, v[236:239]
	v_mfma_f32_16x16x4_f32 v[224:227], v186, v89, v[224:227]
	v_mfma_f32_16x16x4_f32 v[228:231], v187, v89, v[228:231]
	v_mfma_f32_16x16x4_f32 v[232:235], v188, v89, v[232:235]
	v_mfma_f32_16x16x4_f32 v[236:239], v189, v89, v[236:239]
	v_add_u32_e32 v173, 0x880, v173
	v_add_u32_e32 v2, 0x880, v2
	v_add_u32_e32 v3, 0x880, v3
	v_add_u32_e32 v5, 0x880, v5
	ds_read2_b32 v[182:183], v173 offset0:0 offset1:16
	ds_read2_b32 v[184:185], v173 offset0:32 offset1:48
	ds_read2_b32 v[186:187], v2 offset0:0 offset1:16
	ds_read2_b32 v[188:189], v2 offset0:32 offset1:48
	ds_read2_b32 v[190:191], v3 offset0:0 offset1:16
	ds_read2_b32 v[192:193], v3 offset0:32 offset1:48
	ds_read2_b32 v[194:195], v5 offset0:0 offset1:16
	ds_read2_b32 v[196:197], v5 offset0:32 offset1:48
	ds_write2st64_b32 v175, v90, v91 offset0:24 offset1:28
	s_mov_b64 exec, s[14:15]
	ds_add_u32 v179, v241 offset:12
	s_mov_b64 exec, -1
	s_waitcnt lgkmcnt(14)
	v_pk_mul_f32 v[224:225], v[224:225], v[198:199]
	v_pk_mul_f32 v[226:227], v[226:227], v[200:201]
	v_pk_mul_f32 v[228:229], v[228:229], v[202:203]
	v_pk_mul_f32 v[230:231], v[230:231], v[204:205]
	v_mfma_f32_16x16x4_f32 v[36:39], v44, v224, 0
	v_mfma_f32_16x16x4_f32 v[40:43], v45, v225, 0
	v_mfma_f32_16x16x4_f32 v[36:39], v46, v226, v[36:39]
	v_mfma_f32_16x16x4_f32 v[40:43], v47, v227, v[40:43]
	v_pk_mul_f32 v[232:233], v[232:233], v[206:207]
	v_pk_mul_f32 v[234:235], v[234:235], v[208:209]
	v_mfma_f32_16x16x4_f32 v[36:39], v48, v228, v[36:39]
	v_mfma_f32_16x16x4_f32 v[40:43], v49, v229, v[40:43]
	v_mfma_f32_16x16x4_f32 v[36:39], v50, v230, v[36:39]
	v_mfma_f32_16x16x4_f32 v[40:43], v51, v231, v[40:43]
	v_pk_mul_f32 v[236:237], v[236:237], v[210:211]
	v_pk_mul_f32 v[238:239], v[238:239], v[212:213]
	v_mfma_f32_16x16x4_f32 v[36:39], v68, v232, v[36:39]
	v_mfma_f32_16x16x4_f32 v[40:43], v69, v233, v[40:43]
	v_mfma_f32_16x16x4_f32 v[36:39], v70, v234, v[36:39]
	v_mfma_f32_16x16x4_f32 v[40:43], v71, v235, v[40:43]
	v_mfma_f32_16x16x4_f32 v[36:39], v96, v236, v[36:39]
	v_mfma_f32_16x16x4_f32 v[40:43], v97, v237, v[40:43]
	v_mfma_f32_16x16x4_f32 v[36:39], v98, v238, v[36:39]
	v_mfma_f32_16x16x4_f32 v[40:43], v99, v239, v[40:43]
	s_waitcnt lgkmcnt(2)
	v_mfma_f32_16x16x4_f32 v[36:39], v216, v214, v[36:39]
	v_mfma_f32_16x16x4_f32 v[40:43], v217, v215, v[40:43]
	v_mfma_f32_16x16x4_f32 v[224:227], v190, v214, v[224:227]
	v_mfma_f32_16x16x4_f32 v[228:231], v191, v214, v[228:231]
	v_mfma_f32_16x16x4_f32 v[232:235], v192, v214, v[232:235]
	v_mfma_f32_16x16x4_f32 v[236:239], v193, v214, v[236:239]
	ds_read_b128 v[44:47], v168 offset:10880
	ds_read_b128 v[48:51], v168 offset:10944
	ds_read_b128 v[68:71], v168 offset:11008
	ds_read_b128 v[96:99], v168 offset:11072
	ds_read_b32 v216, v171 offset:5376
	ds_read_b32 v217, v171 offset:5392
	v_pk_add_f32 v[84:85], v[36:37], v[40:41]
	v_pk_add_f32 v[82:83], v[38:39], v[42:43]
	s_nop 1
	v_mfma_f32_16x16x4_f32 v[88:91], v218, v84, v[80:83]
	v_mfma_f32_16x16x4_f32 v[88:91], v219, v85, v[88:91]
	v_mfma_f32_16x16x4_f32 v[224:227], v194, v215, v[224:227]
	v_mfma_f32_16x16x4_f32 v[228:231], v195, v215, v[228:231]
	v_mfma_f32_16x16x4_f32 v[232:235], v196, v215, v[232:235]
	v_mfma_f32_16x16x4_f32 v[236:239], v197, v215, v[236:239]
	ds_read_b128 v[198:201], v174 offset:1024
	ds_read_b128 v[202:205], v174 offset:1088
	ds_read_b128 v[206:209], v174 offset:1152
	ds_read_b128 v[210:213], v174 offset:1216
	ds_read_b32 v218, v171 offset:5120
	ds_read_b32 v219, v171 offset:5136
	ds_read_b32 v214, v169 offset:10240
	ds_read_b32 v215, v169 offset:11264
	v_mfma_f32_16x16x4_f32 v[224:227], v182, v88, v[224:227]
	v_mfma_f32_16x16x4_f32 v[228:231], v183, v88, v[228:231]
	v_mfma_f32_16x16x4_f32 v[232:235], v184, v88, v[232:235]
	v_mfma_f32_16x16x4_f32 v[236:239], v185, v88, v[236:239]
	v_mfma_f32_16x16x4_f32 v[224:227], v186, v89, v[224:227]
	v_mfma_f32_16x16x4_f32 v[228:231], v187, v89, v[228:231]
	v_mfma_f32_16x16x4_f32 v[232:235], v188, v89, v[232:235]
	v_mfma_f32_16x16x4_f32 v[236:239], v189, v89, v[236:239]
	v_add_u32_e32 v173, 0x880, v173
	v_add_u32_e32 v2, 0x880, v2
	v_add_u32_e32 v3, 0x880, v3
	v_add_u32_e32 v5, 0x880, v5
	ds_read2_b32 v[182:183], v173 offset0:0 offset1:16
	ds_read2_b32 v[184:185], v173 offset0:32 offset1:48
	ds_read2_b32 v[186:187], v2 offset0:0 offset1:16
	ds_read2_b32 v[188:189], v2 offset0:32 offset1:48
	ds_read2_b32 v[190:191], v3 offset0:0 offset1:16
	ds_read2_b32 v[192:193], v3 offset0:32 offset1:48
	ds_read2_b32 v[194:195], v5 offset0:0 offset1:16
	ds_read2_b32 v[196:197], v5 offset0:32 offset1:48
	ds_write2st64_b32 v175, v90, v91 offset0:32 offset1:36
	s_mov_b64 exec, s[14:15]
	ds_add_u32 v179, v241 offset:16
	s_mov_b64 exec, -1
	s_waitcnt lgkmcnt(14)
	v_pk_mul_f32 v[224:225], v[224:225], v[198:199]
	v_pk_mul_f32 v[226:227], v[226:227], v[200:201]
	v_pk_mul_f32 v[228:229], v[228:229], v[202:203]
	v_pk_mul_f32 v[230:231], v[230:231], v[204:205]
	v_mfma_f32_16x16x4_f32 v[36:39], v44, v224, 0
	v_mfma_f32_16x16x4_f32 v[40:43], v45, v225, 0
	v_mfma_f32_16x16x4_f32 v[36:39], v46, v226, v[36:39]
	v_mfma_f32_16x16x4_f32 v[40:43], v47, v227, v[40:43]
	v_pk_mul_f32 v[232:233], v[232:233], v[206:207]
	v_pk_mul_f32 v[234:235], v[234:235], v[208:209]
	v_mfma_f32_16x16x4_f32 v[36:39], v48, v228, v[36:39]
	v_mfma_f32_16x16x4_f32 v[40:43], v49, v229, v[40:43]
	v_mfma_f32_16x16x4_f32 v[36:39], v50, v230, v[36:39]
	v_mfma_f32_16x16x4_f32 v[40:43], v51, v231, v[40:43]
	v_pk_mul_f32 v[236:237], v[236:237], v[210:211]
	v_pk_mul_f32 v[238:239], v[238:239], v[212:213]
	v_mfma_f32_16x16x4_f32 v[36:39], v68, v232, v[36:39]
	v_mfma_f32_16x16x4_f32 v[40:43], v69, v233, v[40:43]
	v_mfma_f32_16x16x4_f32 v[36:39], v70, v234, v[36:39]
	v_mfma_f32_16x16x4_f32 v[40:43], v71, v235, v[40:43]
	v_mfma_f32_16x16x4_f32 v[36:39], v96, v236, v[36:39]
	v_mfma_f32_16x16x4_f32 v[40:43], v97, v237, v[40:43]
	v_mfma_f32_16x16x4_f32 v[36:39], v98, v238, v[36:39]
	v_mfma_f32_16x16x4_f32 v[40:43], v99, v239, v[40:43]
	s_waitcnt lgkmcnt(2)
	v_mfma_f32_16x16x4_f32 v[36:39], v216, v214, v[36:39]
	v_mfma_f32_16x16x4_f32 v[40:43], v217, v215, v[40:43]
	v_mfma_f32_16x16x4_f32 v[224:227], v190, v214, v[224:227]
	v_mfma_f32_16x16x4_f32 v[228:231], v191, v214, v[228:231]
	v_mfma_f32_16x16x4_f32 v[232:235], v192, v214, v[232:235]
	v_mfma_f32_16x16x4_f32 v[236:239], v193, v214, v[236:239]
	ds_read_b128 v[44:47], v168 offset:13056
	ds_read_b128 v[48:51], v168 offset:13120
	ds_read_b128 v[68:71], v168 offset:13184
	ds_read_b128 v[96:99], v168 offset:13248
	ds_read_b32 v216, v171 offset:6400
	ds_read_b32 v217, v171 offset:6416
	v_pk_add_f32 v[84:85], v[36:37], v[40:41]
	v_pk_add_f32 v[82:83], v[38:39], v[42:43]
	s_nop 1
	v_mfma_f32_16x16x4_f32 v[88:91], v218, v84, v[80:83]
	v_mfma_f32_16x16x4_f32 v[88:91], v219, v85, v[88:91]
	v_mfma_f32_16x16x4_f32 v[224:227], v194, v215, v[224:227]
	v_mfma_f32_16x16x4_f32 v[228:231], v195, v215, v[228:231]
	v_mfma_f32_16x16x4_f32 v[232:235], v196, v215, v[232:235]
	v_mfma_f32_16x16x4_f32 v[236:239], v197, v215, v[236:239]
	ds_read_b128 v[198:201], v174 offset:1280
	ds_read_b128 v[202:205], v174 offset:1344
	ds_read_b128 v[206:209], v174 offset:1408
	ds_read_b128 v[210:213], v174 offset:1472
	ds_read_b32 v218, v171 offset:6144
	ds_read_b32 v219, v171 offset:6160
	ds_read_b32 v214, v169 offset:12288
	ds_read_b32 v215, v169 offset:13312
	v_mfma_f32_16x16x4_f32 v[224:227], v182, v88, v[224:227]
	v_mfma_f32_16x16x4_f32 v[228:231], v183, v88, v[228:231]
	v_mfma_f32_16x16x4_f32 v[232:235], v184, v88, v[232:235]
	v_mfma_f32_16x16x4_f32 v[236:239], v185, v88, v[236:239]
	v_mfma_f32_16x16x4_f32 v[224:227], v186, v89, v[224:227]
	v_mfma_f32_16x16x4_f32 v[228:231], v187, v89, v[228:231]
	v_mfma_f32_16x16x4_f32 v[232:235], v188, v89, v[232:235]
	v_mfma_f32_16x16x4_f32 v[236:239], v189, v89, v[236:239]
	v_add_u32_e32 v173, 0x880, v173
	v_add_u32_e32 v2, 0x880, v2
	v_add_u32_e32 v3, 0x880, v3
	v_add_u32_e32 v5, 0x880, v5
	ds_read2_b32 v[182:183], v173 offset0:0 offset1:16
	ds_read2_b32 v[184:185], v173 offset0:32 offset1:48
	ds_read2_b32 v[186:187], v2 offset0:0 offset1:16
	ds_read2_b32 v[188:189], v2 offset0:32 offset1:48
	ds_read2_b32 v[190:191], v3 offset0:0 offset1:16
	ds_read2_b32 v[192:193], v3 offset0:32 offset1:48
	ds_read2_b32 v[194:195], v5 offset0:0 offset1:16
	ds_read2_b32 v[196:197], v5 offset0:32 offset1:48
	ds_write2st64_b32 v175, v90, v91 offset0:40 offset1:44
	s_mov_b64 exec, s[14:15]
	ds_add_u32 v179, v241 offset:20
	s_mov_b64 exec, -1
	s_waitcnt lgkmcnt(14)
	v_pk_mul_f32 v[224:225], v[224:225], v[198:199]
	v_pk_mul_f32 v[226:227], v[226:227], v[200:201]
	v_pk_mul_f32 v[228:229], v[228:229], v[202:203]
	v_pk_mul_f32 v[230:231], v[230:231], v[204:205]
	v_mfma_f32_16x16x4_f32 v[36:39], v44, v224, 0
	v_mfma_f32_16x16x4_f32 v[40:43], v45, v225, 0
	v_mfma_f32_16x16x4_f32 v[36:39], v46, v226, v[36:39]
	v_mfma_f32_16x16x4_f32 v[40:43], v47, v227, v[40:43]
	v_pk_mul_f32 v[232:233], v[232:233], v[206:207]
	v_pk_mul_f32 v[234:235], v[234:235], v[208:209]
	v_mfma_f32_16x16x4_f32 v[36:39], v48, v228, v[36:39]
	v_mfma_f32_16x16x4_f32 v[40:43], v49, v229, v[40:43]
	v_mfma_f32_16x16x4_f32 v[36:39], v50, v230, v[36:39]
	v_mfma_f32_16x16x4_f32 v[40:43], v51, v231, v[40:43]
	v_pk_mul_f32 v[236:237], v[236:237], v[210:211]
	v_pk_mul_f32 v[238:239], v[238:239], v[212:213]
	v_mfma_f32_16x16x4_f32 v[36:39], v68, v232, v[36:39]
	v_mfma_f32_16x16x4_f32 v[40:43], v69, v233, v[40:43]
	v_mfma_f32_16x16x4_f32 v[36:39], v70, v234, v[36:39]
	v_mfma_f32_16x16x4_f32 v[40:43], v71, v235, v[40:43]
	v_mfma_f32_16x16x4_f32 v[36:39], v96, v236, v[36:39]
	v_mfma_f32_16x16x4_f32 v[40:43], v97, v237, v[40:43]
	v_mfma_f32_16x16x4_f32 v[36:39], v98, v238, v[36:39]
	v_mfma_f32_16x16x4_f32 v[40:43], v99, v239, v[40:43]
	s_waitcnt lgkmcnt(2)
	v_mfma_f32_16x16x4_f32 v[36:39], v216, v214, v[36:39]
	v_mfma_f32_16x16x4_f32 v[40:43], v217, v215, v[40:43]
	v_mfma_f32_16x16x4_f32 v[224:227], v190, v214, v[224:227]
	v_mfma_f32_16x16x4_f32 v[228:231], v191, v214, v[228:231]
	v_mfma_f32_16x16x4_f32 v[232:235], v192, v214, v[232:235]
	v_mfma_f32_16x16x4_f32 v[236:239], v193, v214, v[236:239]
	ds_read_b128 v[44:47], v168 offset:15232
	ds_read_b128 v[48:51], v168 offset:15296
	ds_read_b128 v[68:71], v168 offset:15360
	ds_read_b128 v[96:99], v168 offset:15424
	ds_read_b32 v216, v171 offset:7424
	ds_read_b32 v217, v171 offset:7440
	v_pk_add_f32 v[84:85], v[36:37], v[40:41]
	v_pk_add_f32 v[82:83], v[38:39], v[42:43]
	s_nop 1
	v_mfma_f32_16x16x4_f32 v[88:91], v218, v84, v[80:83]
	v_mfma_f32_16x16x4_f32 v[88:91], v219, v85, v[88:91]
	v_mfma_f32_16x16x4_f32 v[224:227], v194, v215, v[224:227]
	v_mfma_f32_16x16x4_f32 v[228:231], v195, v215, v[228:231]
	v_mfma_f32_16x16x4_f32 v[232:235], v196, v215, v[232:235]
	v_mfma_f32_16x16x4_f32 v[236:239], v197, v215, v[236:239]
	ds_read_b128 v[198:201], v174 offset:1536
	ds_read_b128 v[202:205], v174 offset:1600
	ds_read_b128 v[206:209], v174 offset:1664
	ds_read_b128 v[210:213], v174 offset:1728
	ds_read_b32 v218, v171 offset:7168
	ds_read_b32 v219, v171 offset:7184
	ds_read_b32 v214, v169 offset:14336
	ds_read_b32 v215, v169 offset:15360
	v_mfma_f32_16x16x4_f32 v[224:227], v182, v88, v[224:227]
	v_mfma_f32_16x16x4_f32 v[228:231], v183, v88, v[228:231]
	v_mfma_f32_16x16x4_f32 v[232:235], v184, v88, v[232:235]
	v_mfma_f32_16x16x4_f32 v[236:239], v185, v88, v[236:239]
	v_mfma_f32_16x16x4_f32 v[224:227], v186, v89, v[224:227]
	v_mfma_f32_16x16x4_f32 v[228:231], v187, v89, v[228:231]
	v_mfma_f32_16x16x4_f32 v[232:235], v188, v89, v[232:235]
	v_mfma_f32_16x16x4_f32 v[236:239], v189, v89, v[236:239]
	v_add_u32_e32 v173, 0x880, v173
	v_add_u32_e32 v2, 0x880, v2
	v_add_u32_e32 v3, 0x880, v3
	v_add_u32_e32 v5, 0x880, v5
	ds_read2_b32 v[182:183], v173 offset0:0 offset1:16
	ds_read2_b32 v[184:185], v173 offset0:32 offset1:48
	ds_read2_b32 v[186:187], v2 offset0:0 offset1:16
	ds_read2_b32 v[188:189], v2 offset0:32 offset1:48
	ds_read2_b32 v[190:191], v3 offset0:0 offset1:16
	ds_read2_b32 v[192:193], v3 offset0:32 offset1:48
	ds_read2_b32 v[194:195], v5 offset0:0 offset1:16
	ds_read2_b32 v[196:197], v5 offset0:32 offset1:48
	ds_write2st64_b32 v175, v90, v91 offset0:48 offset1:52
	s_mov_b64 exec, s[14:15]
	ds_add_u32 v179, v241 offset:24
	s_mov_b64 exec, -1
	s_waitcnt lgkmcnt(14)
	v_pk_mul_f32 v[224:225], v[224:225], v[198:199]
	v_pk_mul_f32 v[226:227], v[226:227], v[200:201]
	v_pk_mul_f32 v[228:229], v[228:229], v[202:203]
	v_pk_mul_f32 v[230:231], v[230:231], v[204:205]
	v_mfma_f32_16x16x4_f32 v[36:39], v44, v224, 0
	v_mfma_f32_16x16x4_f32 v[40:43], v45, v225, 0
	v_mfma_f32_16x16x4_f32 v[36:39], v46, v226, v[36:39]
	v_mfma_f32_16x16x4_f32 v[40:43], v47, v227, v[40:43]
	v_pk_mul_f32 v[232:233], v[232:233], v[206:207]
	v_pk_mul_f32 v[234:235], v[234:235], v[208:209]
	v_mfma_f32_16x16x4_f32 v[36:39], v48, v228, v[36:39]
	v_mfma_f32_16x16x4_f32 v[40:43], v49, v229, v[40:43]
	v_mfma_f32_16x16x4_f32 v[36:39], v50, v230, v[36:39]
	v_mfma_f32_16x16x4_f32 v[40:43], v51, v231, v[40:43]
	v_pk_mul_f32 v[236:237], v[236:237], v[210:211]
	v_pk_mul_f32 v[238:239], v[238:239], v[212:213]
	v_mfma_f32_16x16x4_f32 v[36:39], v68, v232, v[36:39]
	v_mfma_f32_16x16x4_f32 v[40:43], v69, v233, v[40:43]
	v_mfma_f32_16x16x4_f32 v[36:39], v70, v234, v[36:39]
	v_mfma_f32_16x16x4_f32 v[40:43], v71, v235, v[40:43]
	v_mfma_f32_16x16x4_f32 v[36:39], v96, v236, v[36:39]
	v_mfma_f32_16x16x4_f32 v[40:43], v97, v237, v[40:43]
	v_mfma_f32_16x16x4_f32 v[36:39], v98, v238, v[36:39]
	v_mfma_f32_16x16x4_f32 v[40:43], v99, v239, v[40:43]
	s_waitcnt lgkmcnt(2)
	v_mfma_f32_16x16x4_f32 v[36:39], v216, v214, v[36:39]
	v_mfma_f32_16x16x4_f32 v[40:43], v217, v215, v[40:43]
	v_mfma_f32_16x16x4_f32 v[224:227], v190, v214, v[224:227]
	v_mfma_f32_16x16x4_f32 v[228:231], v191, v214, v[228:231]
	v_mfma_f32_16x16x4_f32 v[232:235], v192, v214, v[232:235]
	v_mfma_f32_16x16x4_f32 v[236:239], v193, v214, v[236:239]
	ds_read_b128 v[44:47], v168 offset:17408
	ds_read_b128 v[48:51], v168 offset:17472
	ds_read_b128 v[68:71], v168 offset:17536
	ds_read_b128 v[96:99], v168 offset:17600
	ds_read_b32 v216, v171 offset:8448
	ds_read_b32 v217, v171 offset:8464
	v_pk_add_f32 v[84:85], v[36:37], v[40:41]
	v_pk_add_f32 v[82:83], v[38:39], v[42:43]
	s_nop 1
	v_mfma_f32_16x16x4_f32 v[88:91], v218, v84, v[80:83]
	v_mfma_f32_16x16x4_f32 v[88:91], v219, v85, v[88:91]
	v_mfma_f32_16x16x4_f32 v[224:227], v194, v215, v[224:227]
	v_mfma_f32_16x16x4_f32 v[228:231], v195, v215, v[228:231]
	v_mfma_f32_16x16x4_f32 v[232:235], v196, v215, v[232:235]
	v_mfma_f32_16x16x4_f32 v[236:239], v197, v215, v[236:239]
	ds_read_b128 v[198:201], v174 offset:1792
	ds_read_b128 v[202:205], v174 offset:1856
	ds_read_b128 v[206:209], v174 offset:1920
	ds_read_b128 v[210:213], v174 offset:1984
	ds_read_b32 v218, v171 offset:8192
	ds_read_b32 v219, v171 offset:8208
	ds_read_b32 v214, v169 offset:16384
	ds_read_b32 v215, v169 offset:17408
	v_mfma_f32_16x16x4_f32 v[224:227], v182, v88, v[224:227]
	v_mfma_f32_16x16x4_f32 v[228:231], v183, v88, v[228:231]
	v_mfma_f32_16x16x4_f32 v[232:235], v184, v88, v[232:235]
	v_mfma_f32_16x16x4_f32 v[236:239], v185, v88, v[236:239]
	v_mfma_f32_16x16x4_f32 v[224:227], v186, v89, v[224:227]
	v_mfma_f32_16x16x4_f32 v[228:231], v187, v89, v[228:231]
	v_mfma_f32_16x16x4_f32 v[232:235], v188, v89, v[232:235]
	v_mfma_f32_16x16x4_f32 v[236:239], v189, v89, v[236:239]
	v_add_u32_e32 v173, 0x880, v173
	v_add_u32_e32 v2, 0x880, v2
	v_add_u32_e32 v3, 0x880, v3
	v_add_u32_e32 v5, 0x880, v5
	ds_read2_b32 v[182:183], v173 offset0:0 offset1:16
	ds_read2_b32 v[184:185], v173 offset0:32 offset1:48
	ds_read2_b32 v[186:187], v2 offset0:0 offset1:16
	ds_read2_b32 v[188:189], v2 offset0:32 offset1:48
	ds_read2_b32 v[190:191], v3 offset0:0 offset1:16
	ds_read2_b32 v[192:193], v3 offset0:32 offset1:48
	ds_read2_b32 v[194:195], v5 offset0:0 offset1:16
	ds_read2_b32 v[196:197], v5 offset0:32 offset1:48
	ds_write2st64_b32 v175, v90, v91 offset0:56 offset1:60
	s_mov_b64 exec, s[14:15]
	ds_add_u32 v179, v241 offset:28
	s_mov_b64 exec, -1
	s_waitcnt lgkmcnt(0)
	s_nop 7
	v_pk_mul_f32 v[224:225], v[224:225], v[198:199]
	v_pk_mul_f32 v[226:227], v[226:227], v[200:201]
	v_pk_mul_f32 v[228:229], v[228:229], v[202:203]
	v_pk_mul_f32 v[230:231], v[230:231], v[204:205]
	v_pk_mul_f32 v[232:233], v[232:233], v[206:207]
	v_pk_mul_f32 v[234:235], v[234:235], v[208:209]
	v_pk_mul_f32 v[236:237], v[236:237], v[210:211]
	v_pk_mul_f32 v[238:239], v[238:239], v[212:213]
	s_branch .Lrw_done
